# residual GEMM epilogue (out = sqrt2*x + gate*acc): 16 x loads issued up front with counted vmcnt waits
# speedup vs baseline: 1.0213x; 1.0040x over previous
.LBB0_1406:
	s_cmp_lt_u32 s26, 10
	s_cselect_b32 s0, s41, s43
	v_mov_b32_e32 v79, s0
	s_movk_i32 s0, 0x180
	s_cselect_b32 s0, s0, 0x500
	v_mad_i64_i32 v[80:81], s[30:31], s0, v64, 0
	s_cselect_b32 s29, s40, s42
	s_cselect_b32 s30, 0, 0xfffffe80
	v_mov_b32_e32 v78, s29
	s_cselect_b32 s29, 0, -1
	s_add_u32 s30, s10, s30
	v_lshl_add_u64 v[78:79], v[80:81], 1, v[78:79]
	s_addc_u32 s31, s11, s29
	v_lshl_add_u64 v[78:79], s[30:31], 1, v[78:79]
	s_lshl_b32 s29, s28, 14
	s_waitcnt vmcnt(0)
	v_lshl_add_u64 v[82:83], v[78:79], 0, v[68:69]
	s_add_i32 s29, s14, s29
	s_lshl_b32 s0, s0, 5
	s_waitcnt lgkmcnt(0)
	s_barrier
	v_lshl_add_u64 v[78:79], v[82:83], 0, s[4:5]
	s_mov_b32 m0, s29
	v_lshl_add_u64 v[120:121], v[82:83], 0, s[0:1]
	global_load_lds_dwordx4 v[78:79], off
	v_lshl_add_u64 v[78:79], v[120:121], 0, s[4:5]
	s_add_i32 m0, s29, 0x400
	v_lshl_add_u64 v[122:123], v[66:67], 0, s[12:13]
	global_load_lds_dwordx4 v[78:79], off
	s_add_i32 m0, s29, 0x2000
	v_lshl_add_u64 v[78:79], v[122:123], 0, s[4:5]
	s_lshl_b32 s0, s27, 14
	global_load_lds_dwordx4 v[78:79], off
	s_add_i32 m0, s29, 0x2400
	v_add_u32_e32 v65, s0, v88
	v_or_b32_e32 v124, s0, v89
	s_add_i32 s0, s27, 1
	s_cmp_lg_u32 s27, 3
	s_mov_b64 s[30:31], 0x8080
	s_cselect_b32 s27, s0, 0
	s_add_i32 s0, s28, 1
	v_lshl_add_u64 v[78:79], v[122:123], 0, s[30:31]
	s_cmp_lg_u32 s28, 3
	global_load_lds_dwordx4 v[78:79], off
	s_cselect_b32 s0, s0, 0
	ds_read_b128 v[78:81], v65
	ds_read_b128 v[92:95], v65 offset:1024
	ds_read_b128 v[96:99], v65 offset:2048
	ds_read_b128 v[100:103], v65 offset:3072
	ds_read_b128 v[104:107], v124
	ds_read_b128 v[108:111], v124 offset:1024
	ds_read_b128 v[112:115], v124 offset:2048
	ds_read_b128 v[116:119], v124 offset:3072
	s_waitcnt lgkmcnt(0)
	s_lshl_b32 s28, s0, 14
	s_add_i32 s30, s14, s28
	v_mfma_f32_16x16x32_bf16 v[60:63], v[104:107], v[78:81], v[60:63]
	v_mfma_f32_16x16x32_bf16 v[56:59], v[108:111], v[78:81], v[56:59]
	s_mov_b32 m0, s30
	s_mov_b64 s[28:29], 0x80c0
	s_add_i32 s26, s26, 2
	v_mfma_f32_16x16x32_bf16 v[52:55], v[112:115], v[78:81], v[52:55]
	v_mfma_f32_16x16x32_bf16 v[48:51], v[116:119], v[78:81], v[48:51]
	v_lshl_add_u64 v[78:79], v[82:83], 0, s[6:7]
	global_load_lds_dwordx4 v[78:79], off
	v_lshl_add_u64 v[78:79], v[120:121], 0, s[6:7]
	s_add_i32 m0, s30, 0x400
	v_mfma_f32_16x16x32_bf16 v[44:47], v[104:107], v[92:95], v[44:47]
	global_load_lds_dwordx4 v[78:79], off
	s_add_i32 m0, s30, 0x2000
	v_lshl_add_u64 v[78:79], v[122:123], 0, s[6:7]
	global_load_lds_dwordx4 v[78:79], off
	v_lshl_add_u64 v[78:79], v[122:123], 0, s[28:29]
	s_add_i32 m0, s30, 0x2400
	s_lshl_b32 s28, s27, 14
	global_load_lds_dwordx4 v[78:79], off
	v_add_u32_e32 v65, s28, v88
	v_or_b32_e32 v82, s28, v89
	s_add_i32 s28, s27, 1
	v_mfma_f32_16x16x32_bf16 v[40:43], v[108:111], v[92:95], v[40:43]
	s_cmp_lg_u32 s27, 3
	s_cselect_b32 s27, s28, 0
	s_add_i32 s28, s0, 1
	v_mfma_f32_16x16x32_bf16 v[36:39], v[112:115], v[92:95], v[36:39]
	s_cmp_lg_u32 s0, 3
	s_cselect_b32 s28, s28, 0
	s_add_u32 s12, s12, 0x80
	v_mfma_f32_16x16x32_bf16 v[32:35], v[116:119], v[92:95], v[32:35]
	s_addc_u32 s13, s13, 0
	s_add_u32 s10, s10, 64
	s_addc_u32 s11, s11, 0
	v_mfma_f32_16x16x32_bf16 v[28:31], v[104:107], v[96:99], v[28:31]
	s_cmpk_eq_i32 s12, 0x780
	v_mfma_f32_16x16x32_bf16 v[24:27], v[108:111], v[96:99], v[24:27]
	v_mfma_f32_16x16x32_bf16 v[20:23], v[112:115], v[96:99], v[20:23]
	v_mfma_f32_16x16x32_bf16 v[16:19], v[116:119], v[96:99], v[16:19]
	v_mfma_f32_16x16x32_bf16 v[12:15], v[104:107], v[100:103], v[12:15]
	v_mfma_f32_16x16x32_bf16 v[8:11], v[108:111], v[100:103], v[8:11]
	v_mfma_f32_16x16x32_bf16 v[4:7], v[112:115], v[100:103], v[4:7]
	v_mfma_f32_16x16x32_bf16 v[0:3], v[116:119], v[100:103], v[0:3]
	ds_read_b128 v[78:81], v65
	ds_read_b128 v[92:95], v65 offset:1024
	ds_read_b128 v[96:99], v65 offset:2048
	ds_read_b128 v[100:103], v65 offset:3072
	ds_read_b128 v[104:107], v82
	ds_read_b128 v[108:111], v82 offset:1024
	ds_read_b128 v[112:115], v82 offset:2048
	ds_read_b128 v[116:119], v82 offset:3072
	s_waitcnt lgkmcnt(0)
	s_nop 0
	v_mfma_f32_16x16x32_bf16 v[60:63], v[104:107], v[78:81], v[60:63]
	v_mfma_f32_16x16x32_bf16 v[56:59], v[108:111], v[78:81], v[56:59]
	v_mfma_f32_16x16x32_bf16 v[52:55], v[112:115], v[78:81], v[52:55]
	v_mfma_f32_16x16x32_bf16 v[48:51], v[116:119], v[78:81], v[48:51]
	v_mfma_f32_16x16x32_bf16 v[44:47], v[104:107], v[92:95], v[44:47]
	v_mfma_f32_16x16x32_bf16 v[40:43], v[108:111], v[92:95], v[40:43]
	v_mfma_f32_16x16x32_bf16 v[36:39], v[112:115], v[92:95], v[36:39]
	v_mfma_f32_16x16x32_bf16 v[32:35], v[116:119], v[92:95], v[32:35]
	v_mfma_f32_16x16x32_bf16 v[28:31], v[104:107], v[96:99], v[28:31]
	v_mfma_f32_16x16x32_bf16 v[24:27], v[108:111], v[96:99], v[24:27]
	v_mfma_f32_16x16x32_bf16 v[20:23], v[112:115], v[96:99], v[20:23]
	v_mfma_f32_16x16x32_bf16 v[16:19], v[116:119], v[96:99], v[16:19]
	v_mfma_f32_16x16x32_bf16 v[12:15], v[104:107], v[100:103], v[12:15]
	v_mfma_f32_16x16x32_bf16 v[8:11], v[108:111], v[100:103], v[8:11]
	v_mfma_f32_16x16x32_bf16 v[4:7], v[112:115], v[100:103], v[4:7]
	v_mfma_f32_16x16x32_bf16 v[0:3], v[116:119], v[100:103], v[0:3]
	s_cbranch_scc0 .LBB0_1406
	s_waitcnt vmcnt(4)
	s_waitcnt lgkmcnt(0)
	s_barrier
	ds_read_b128 v[64:67], v88 offset:32768
	ds_read_b128 v[78:81], v88 offset:33792
	ds_read_b128 v[92:95], v88 offset:34816
	ds_read_b128 v[96:99], v88 offset:35840
	ds_read_b128 v[100:103], v89 offset:32768
	ds_read_b128 v[104:107], v89 offset:33792
	ds_read_b128 v[108:111], v89 offset:34816
	ds_read_b128 v[112:115], v89 offset:35840
	s_waitcnt lgkmcnt(0)
	s_waitcnt vmcnt(0)
	s_waitcnt lgkmcnt(0)
	s_barrier
	v_mfma_f32_16x16x32_bf16 v[56:59], v[104:107], v[64:67], v[56:59]
	s_movk_i32 s0, 0xfff
	v_readlane_b32 s36, v241, 1
	v_mfma_f32_16x16x32_bf16 v[40:43], v[104:107], v[78:81], v[40:43]
	v_readlane_b32 s44, v241, 9
	v_readlane_b32 s45, v241, 10
	s_add_i32 s2, s2, s3
	v_mfma_f32_16x16x32_bf16 v[24:27], v[104:107], v[92:95], v[24:27]
	s_add_i32 s15, s15, s16
	s_cmpk_gt_i32 s2, 0x9f
	v_readlane_b32 s37, v241, 2
	v_mfma_f32_16x16x32_bf16 v[52:55], v[108:111], v[64:67], v[52:55]
	v_readlane_b32 s38, v241, 3
	v_readlane_b32 s39, v241, 4
	v_readlane_b32 s40, v241, 5
	v_mfma_f32_16x16x32_bf16 v[36:39], v[108:111], v[78:81], v[36:39]
	v_readlane_b32 s41, v241, 6
	v_readlane_b32 s42, v241, 7
	v_readlane_b32 s43, v241, 8
	v_mfma_f32_16x16x32_bf16 v[20:23], v[108:111], v[92:95], v[20:23]
	v_readlane_b32 s46, v241, 11
	v_readlane_b32 s47, v241, 12
	v_readlane_b32 s48, v241, 13
	v_mfma_f32_16x16x32_bf16 v[60:63], v[100:103], v[64:67], v[60:63]
	v_readlane_b32 s49, v241, 14
	v_readlane_b32 s50, v241, 15
	v_readlane_b32 s51, v241, 16
	v_mfma_f32_16x16x32_bf16 v[48:51], v[112:115], v[64:67], v[48:51]
	v_mfma_f32_16x16x32_bf16 v[44:47], v[100:103], v[78:81], v[44:47]
	v_mfma_f32_16x16x32_bf16 v[32:35], v[112:115], v[78:81], v[32:35]
	v_mfma_f32_16x16x32_bf16 v[28:31], v[100:103], v[92:95], v[28:31]
	v_mfma_f32_16x16x32_bf16 v[16:19], v[112:115], v[92:95], v[16:19]
	v_mfma_f32_16x16x32_bf16 v[12:15], v[100:103], v[96:99], v[12:15]
	v_mfma_f32_16x16x32_bf16 v[8:11], v[104:107], v[96:99], v[8:11]
	v_mfma_f32_16x16x32_bf16 v[4:7], v[108:111], v[96:99], v[4:7]
	v_mfma_f32_16x16x32_bf16 v[0:3], v[112:115], v[96:99], v[0:3]
	ds_read_b128 v[64:67], v88 offset:49152
	ds_read_b128 v[78:81], v88 offset:50176
	ds_read_b128 v[92:95], v88 offset:51200
	ds_read_b128 v[96:99], v88 offset:52224
	ds_read_b128 v[100:103], v89 offset:49152
	ds_read_b128 v[104:107], v89 offset:50176
	ds_read_b128 v[108:111], v89 offset:51200
	ds_read_b128 v[112:115], v89 offset:52224
	s_waitcnt lgkmcnt(0)
	s_waitcnt lgkmcnt(0)
	s_barrier
	v_mfma_f32_16x16x32_bf16 v[120:123], v[104:107], v[64:67], v[56:59]
	v_mfma_f32_16x16x32_bf16 v[56:59], v[104:107], v[78:81], v[40:43]
	v_mfma_f32_16x16x32_bf16 v[40:43], v[104:107], v[92:95], v[24:27]
	s_nop 2
	v_add_u32_e32 v24, s24, v86
	v_mfma_f32_16x16x32_bf16 v[124:127], v[108:111], v[64:67], v[52:55]
	v_cmp_lt_i32_e32 vcc, s0, v24
	s_movk_i32 s0, 0x6000
	v_mfma_f32_16x16x32_bf16 v[52:55], v[108:111], v[78:81], v[36:39]
	v_mfma_f32_16x16x32_bf16 v[36:39], v[108:111], v[92:95], v[20:23]
	s_nop 2
	v_add_u32_e32 v21, 0xfffff000, v24
	v_lshrrev_b32_e32 v21, 12, v21
	v_add_u32_e32 v21, 1, v21
	v_or_b32_e32 v20, s25, v87
	v_cndmask_b32_e32 v21, 0, v21, vcc
	v_mad_u64_u32 v[22:23], s[10:11], v21, s0, v[74:75]
	v_ashrrev_i32_e32 v21, 31, v20
	v_mfma_f32_16x16x32_bf16 v[116:119], v[100:103], v[64:67], v[60:63]
	s_mov_b64 s[10:11], 0x2000
	s_movk_i32 s0, 0x2000
	v_mfma_f32_16x16x32_bf16 v[64:67], v[112:115], v[64:67], v[48:51]
	v_mfma_f32_16x16x32_bf16 v[60:63], v[100:103], v[78:81], v[44:47]
	v_mfma_f32_16x16x32_bf16 v[48:51], v[112:115], v[78:81], v[32:35]
	v_lshlrev_b64 v[78:79], 2, v[20:21]
	v_lshl_add_u64 v[20:21], v[22:23], 0, v[78:79]
	v_lshl_add_u64 v[20:21], v[20:21], 0, v[76:77]
	v_lshl_add_u64 v[22:23], v[20:21], 0, s[10:11]
	v_add_co_u32_e32 v20, vcc, s0, v20
	v_mfma_f32_16x16x32_bf16 v[44:47], v[100:103], v[92:95], v[28:31]
	s_nop 0
	v_addc_co_u32_e32 v21, vcc, 0, v21, vcc
	v_mfma_f32_16x16x32_bf16 v[16:19], v[112:115], v[92:95], v[16:19]
	v_or_b32_e32 v92, v24, v84
	v_or_b32_e32 v82, 32, v92
	v_or_b32_e32 v80, 48, v92
	v_mfma_f32_16x16x32_bf16 v[12:15], v[100:103], v[96:99], v[12:15]
	global_load_dwordx4 v[32:35], v[20:21], off
	global_load_dwordx4 v[28:31], v[22:23], off offset:64
	global_load_dwordx4 v[24:27], v[22:23], off offset:128
	s_nop 0
	global_load_dwordx4 v[20:23], v[22:23], off offset:192
	v_mfma_f32_16x16x32_bf16 v[8:11], v[104:107], v[96:99], v[8:11]
	v_mfma_f32_16x16x32_bf16 v[4:7], v[108:111], v[96:99], v[4:7]
	v_mfma_f32_16x16x32_bf16 v[0:3], v[112:115], v[96:99], v[0:3]
	v_or_b32_e32 v96, 16, v92
	s_nop 0
	v_mov_b32_e32 v192, v92
	v_ashrrev_i32_e32 v193, 31, v92
	v_lshlrev_b64 v[192:193], 12, v[192:193]
	v_lshl_add_u64 v[192:193], s[44:45], 0, v[192:193]
	v_lshl_add_u64 v[192:193], v[192:193], 0, v[78:79]
	v_lshl_add_u64 v[192:193], v[192:193], 0, v[76:77]
	v_mov_b32_e32 v194, v96
	v_ashrrev_i32_e32 v195, 31, v96
	v_lshlrev_b64 v[194:195], 12, v[194:195]
	v_lshl_add_u64 v[194:195], s[44:45], 0, v[194:195]
	v_lshl_add_u64 v[194:195], v[194:195], 0, v[78:79]
	v_lshl_add_u64 v[194:195], v[194:195], 0, v[76:77]
	v_mov_b32_e32 v196, v82
	v_ashrrev_i32_e32 v197, 31, v82
	v_lshlrev_b64 v[196:197], 12, v[196:197]
	v_lshl_add_u64 v[196:197], s[44:45], 0, v[196:197]
	v_lshl_add_u64 v[196:197], v[196:197], 0, v[78:79]
	v_lshl_add_u64 v[196:197], v[196:197], 0, v[76:77]
	v_mov_b32_e32 v198, v80
	v_ashrrev_i32_e32 v199, 31, v80
	v_lshlrev_b64 v[198:199], 12, v[198:199]
	v_lshl_add_u64 v[198:199], s[44:45], 0, v[198:199]
	v_lshl_add_u64 v[198:199], v[198:199], 0, v[78:79]
	v_lshl_add_u64 v[198:199], v[198:199], 0, v[76:77]
	global_load_dwordx4 v[128:131], v[192:193], off
	global_load_dwordx4 v[132:135], v[192:193], off offset:64
	global_load_dwordx4 v[136:139], v[192:193], off offset:128
	global_load_dwordx4 v[140:143], v[192:193], off offset:192
	global_load_dwordx4 v[144:147], v[194:195], off
	global_load_dwordx4 v[148:151], v[194:195], off offset:64
	global_load_dwordx4 v[152:155], v[194:195], off offset:128
	global_load_dwordx4 v[156:159], v[194:195], off offset:192
	global_load_dwordx4 v[160:163], v[196:197], off
	global_load_dwordx4 v[164:167], v[196:197], off offset:64
	global_load_dwordx4 v[168:171], v[196:197], off offset:128
	global_load_dwordx4 v[172:175], v[196:197], off offset:192
	global_load_dwordx4 v[176:179], v[198:199], off
	global_load_dwordx4 v[180:183], v[198:199], off offset:64
	global_load_dwordx4 v[184:187], v[198:199], off offset:128
	global_load_dwordx4 v[188:191], v[198:199], off offset:192
	s_waitcnt vmcnt(15)
	v_pk_mul_f32 v[128:129], v[128:129], s[8:9] op_sel_hi:[1,0]
	v_pk_mul_f32 v[130:131], v[130:131], s[8:9] op_sel_hi:[1,0]
	v_pk_fma_f32 v[128:129], v[116:117], v[32:33], v[128:129]
	v_pk_fma_f32 v[130:131], v[118:119], v[34:35], v[130:131]
	global_store_dwordx4 v[192:193], v[128:131], off
	s_waitcnt vmcnt(15)
	v_pk_mul_f32 v[132:133], v[132:133], s[8:9] op_sel_hi:[1,0]
	v_pk_mul_f32 v[134:135], v[134:135], s[8:9] op_sel_hi:[1,0]
	v_pk_fma_f32 v[132:133], v[120:121], v[28:29], v[132:133]
	v_pk_fma_f32 v[134:135], v[122:123], v[30:31], v[134:135]
	global_store_dwordx4 v[192:193], v[132:135], off offset:64
	s_waitcnt vmcnt(15)
	v_pk_mul_f32 v[136:137], v[136:137], s[8:9] op_sel_hi:[1,0]
	v_pk_mul_f32 v[138:139], v[138:139], s[8:9] op_sel_hi:[1,0]
	v_pk_fma_f32 v[136:137], v[124:125], v[24:25], v[136:137]
	v_pk_fma_f32 v[138:139], v[126:127], v[26:27], v[138:139]
	global_store_dwordx4 v[192:193], v[136:139], off offset:128
	s_waitcnt vmcnt(15)
	v_pk_mul_f32 v[140:141], v[140:141], s[8:9] op_sel_hi:[1,0]
	v_pk_fma_f32 v[64:65], v[64:65], v[20:21], v[140:141]
	v_pk_mul_f32 v[140:141], v[142:143], s[8:9] op_sel_hi:[1,0]
	v_pk_fma_f32 v[66:67], v[66:67], v[22:23], v[140:141]
	global_store_dwordx4 v[192:193], v[64:67], off offset:192
	s_waitcnt vmcnt(15)
	v_pk_mul_f32 v[144:145], v[144:145], s[8:9] op_sel_hi:[1,0]
	v_pk_fma_f32 v[60:61], v[60:61], v[32:33], v[144:145]
	v_pk_mul_f32 v[144:145], v[146:147], s[8:9] op_sel_hi:[1,0]
	v_pk_fma_f32 v[62:63], v[62:63], v[34:35], v[144:145]
	global_store_dwordx4 v[194:195], v[60:63], off
	s_waitcnt vmcnt(15)
	v_pk_mul_f32 v[148:149], v[148:149], s[8:9] op_sel_hi:[1,0]
	v_pk_fma_f32 v[56:57], v[56:57], v[28:29], v[148:149]
	v_pk_mul_f32 v[148:149], v[150:151], s[8:9] op_sel_hi:[1,0]
	v_pk_fma_f32 v[58:59], v[58:59], v[30:31], v[148:149]
	global_store_dwordx4 v[194:195], v[56:59], off offset:64
	s_waitcnt vmcnt(15)
	v_pk_mul_f32 v[152:153], v[152:153], s[8:9] op_sel_hi:[1,0]
	v_pk_fma_f32 v[52:53], v[52:53], v[24:25], v[152:153]
	v_pk_mul_f32 v[152:153], v[154:155], s[8:9] op_sel_hi:[1,0]
	v_pk_fma_f32 v[54:55], v[54:55], v[26:27], v[152:153]
	global_store_dwordx4 v[194:195], v[52:55], off offset:128
	s_waitcnt vmcnt(15)
	v_pk_mul_f32 v[156:157], v[156:157], s[8:9] op_sel_hi:[1,0]
	v_pk_fma_f32 v[48:49], v[48:49], v[20:21], v[156:157]
	v_pk_mul_f32 v[156:157], v[158:159], s[8:9] op_sel_hi:[1,0]
	v_pk_fma_f32 v[50:51], v[50:51], v[22:23], v[156:157]
	global_store_dwordx4 v[194:195], v[48:51], off offset:192
	s_waitcnt vmcnt(15)
	v_pk_mul_f32 v[160:161], v[160:161], s[8:9] op_sel_hi:[1,0]
	v_pk_fma_f32 v[44:45], v[44:45], v[32:33], v[160:161]
	v_pk_mul_f32 v[160:161], v[162:163], s[8:9] op_sel_hi:[1,0]
	v_pk_fma_f32 v[46:47], v[46:47], v[34:35], v[160:161]
	global_store_dwordx4 v[196:197], v[44:47], off
	s_waitcnt vmcnt(15)
	v_pk_mul_f32 v[164:165], v[164:165], s[8:9] op_sel_hi:[1,0]
	v_pk_fma_f32 v[40:41], v[40:41], v[28:29], v[164:165]
	v_pk_mul_f32 v[164:165], v[166:167], s[8:9] op_sel_hi:[1,0]
	v_pk_fma_f32 v[42:43], v[42:43], v[30:31], v[164:165]
	global_store_dwordx4 v[196:197], v[40:43], off offset:64
	s_waitcnt vmcnt(15)
	v_pk_mul_f32 v[168:169], v[168:169], s[8:9] op_sel_hi:[1,0]
	v_pk_fma_f32 v[36:37], v[36:37], v[24:25], v[168:169]
	v_pk_mul_f32 v[168:169], v[170:171], s[8:9] op_sel_hi:[1,0]
	v_pk_fma_f32 v[38:39], v[38:39], v[26:27], v[168:169]
	global_store_dwordx4 v[196:197], v[36:39], off offset:128
	s_waitcnt vmcnt(15)
	v_pk_mul_f32 v[172:173], v[172:173], s[8:9] op_sel_hi:[1,0]
	v_pk_fma_f32 v[16:17], v[16:17], v[20:21], v[172:173]
	v_pk_mul_f32 v[172:173], v[174:175], s[8:9] op_sel_hi:[1,0]
	v_pk_fma_f32 v[18:19], v[18:19], v[22:23], v[172:173]
	global_store_dwordx4 v[196:197], v[16:19], off offset:192
	s_waitcnt vmcnt(15)
	v_pk_mul_f32 v[176:177], v[176:177], s[8:9] op_sel_hi:[1,0]
	v_pk_fma_f32 v[12:13], v[12:13], v[32:33], v[176:177]
	v_pk_mul_f32 v[176:177], v[178:179], s[8:9] op_sel_hi:[1,0]
	v_pk_fma_f32 v[14:15], v[14:15], v[34:35], v[176:177]
	global_store_dwordx4 v[198:199], v[12:15], off
	s_waitcnt vmcnt(15)
	v_pk_mul_f32 v[180:181], v[180:181], s[8:9] op_sel_hi:[1,0]
	v_pk_fma_f32 v[8:9], v[8:9], v[28:29], v[180:181]
	v_pk_mul_f32 v[180:181], v[182:183], s[8:9] op_sel_hi:[1,0]
	v_pk_fma_f32 v[10:11], v[10:11], v[30:31], v[180:181]
	global_store_dwordx4 v[198:199], v[8:11], off offset:64
	s_waitcnt vmcnt(15)
	v_pk_mul_f32 v[184:185], v[184:185], s[8:9] op_sel_hi:[1,0]
	v_pk_fma_f32 v[4:5], v[4:5], v[24:25], v[184:185]
	v_pk_mul_f32 v[184:185], v[186:187], s[8:9] op_sel_hi:[1,0]
	v_pk_fma_f32 v[6:7], v[6:7], v[26:27], v[184:185]
	global_store_dwordx4 v[198:199], v[4:7], off offset:128
	s_waitcnt vmcnt(15)
	v_pk_mul_f32 v[188:189], v[188:189], s[8:9] op_sel_hi:[1,0]
	v_pk_fma_f32 v[0:1], v[0:1], v[20:21], v[188:189]
	v_pk_mul_f32 v[188:189], v[190:191], s[8:9] op_sel_hi:[1,0]
	v_pk_fma_f32 v[2:3], v[2:3], v[22:23], v[188:189]
	global_store_dwordx4 v[198:199], v[0:3], off offset:192
	s_cbranch_scc0 .LBB0_1405

.LBB0_1577:
	s_lshl_b32 s36, s35, 14
	s_waitcnt vmcnt(0)
	v_lshl_add_u64 v[80:81], v[66:67], 0, s[16:17]
	s_add_i32 s36, s19, s36
	s_waitcnt lgkmcnt(0)
	s_barrier
	v_lshl_add_u64 v[76:77], v[80:81], 0, s[6:7]
	s_mov_b32 m0, s36
	v_lshl_add_u64 v[118:119], v[64:65], 0, s[16:17]
	global_load_lds_dwordx4 v[76:77], off
	v_lshl_add_u64 v[76:77], v[80:81], 0, s[8:9]
	s_add_i32 m0, s36, 0x400
	s_nop 0
	global_load_lds_dwordx4 v[76:77], off
	s_add_i32 m0, s36, 0x2000
	v_lshl_add_u64 v[76:77], v[118:119], 0, s[6:7]
	global_load_lds_dwordx4 v[76:77], off
	s_add_i32 m0, s36, 0x2400
	s_lshl_b32 s36, s34, 14
	v_add_u32_e32 v120, s36, v86
	v_or_b32_e32 v121, s36, v87
	s_add_i32 s36, s34, 1
	s_cmp_lg_u32 s34, 3
	s_cselect_b32 s34, s36, 0
	s_add_i32 s36, s35, 1
	v_lshl_add_u64 v[76:77], v[118:119], 0, s[8:9]
	s_cmp_lg_u32 s35, 3
	global_load_lds_dwordx4 v[76:77], off
	s_cselect_b32 s35, s36, 0
	ds_read_b128 v[76:79], v120
	ds_read_b128 v[90:93], v120 offset:1024
	ds_read_b128 v[94:97], v120 offset:2048
	ds_read_b128 v[98:101], v120 offset:3072
	ds_read_b128 v[102:105], v121
	ds_read_b128 v[106:109], v121 offset:1024
	ds_read_b128 v[110:113], v121 offset:2048
	ds_read_b128 v[114:117], v121 offset:3072
	s_waitcnt lgkmcnt(0)
	s_lshl_b32 s36, s35, 14
	s_add_i32 s36, s19, s36
	v_mfma_f32_16x16x32_bf16 v[60:63], v[102:105], v[76:79], v[60:63]
	v_mfma_f32_16x16x32_bf16 v[56:59], v[106:109], v[76:79], v[56:59]
	s_mov_b32 m0, s36
	v_mfma_f32_16x16x32_bf16 v[52:55], v[110:113], v[76:79], v[52:55]
	v_mfma_f32_16x16x32_bf16 v[48:51], v[114:117], v[76:79], v[48:51]
	v_lshl_add_u64 v[76:77], v[80:81], 0, s[10:11]
	global_load_lds_dwordx4 v[76:77], off
	v_lshl_add_u64 v[76:77], v[80:81], 0, s[12:13]
	s_add_i32 m0, s36, 0x400
	v_mfma_f32_16x16x32_bf16 v[44:47], v[102:105], v[90:93], v[44:47]
	global_load_lds_dwordx4 v[76:77], off
	s_add_i32 m0, s36, 0x2000
	v_lshl_add_u64 v[76:77], v[118:119], 0, s[10:11]
	global_load_lds_dwordx4 v[76:77], off
	v_lshl_add_u64 v[76:77], v[118:119], 0, s[12:13]
	s_add_i32 m0, s36, 0x2400
	v_mfma_f32_16x16x32_bf16 v[40:43], v[106:109], v[90:93], v[40:43]
	global_load_lds_dwordx4 v[76:77], off
	s_lshl_b32 s36, s34, 14
	v_mfma_f32_16x16x32_bf16 v[36:39], v[110:113], v[90:93], v[36:39]
	v_add_u32_e32 v80, s36, v86
	v_or_b32_e32 v81, s36, v87
	s_add_i32 s36, s34, 1
	v_mfma_f32_16x16x32_bf16 v[32:35], v[114:117], v[90:93], v[32:35]
	s_cmp_lg_u32 s34, 3
	s_cselect_b32 s34, s36, 0
	s_add_i32 s36, s35, 1
	v_mfma_f32_16x16x32_bf16 v[28:31], v[102:105], v[94:97], v[28:31]
	s_cmp_lg_u32 s35, 3
	s_cselect_b32 s35, s36, 0
	s_add_u32 s16, s16, 0x80
	v_mfma_f32_16x16x32_bf16 v[24:27], v[106:109], v[94:97], v[24:27]
	s_addc_u32 s17, s17, 0
	s_cmpk_eq_i32 s16, 0x1580
	v_mfma_f32_16x16x32_bf16 v[20:23], v[110:113], v[94:97], v[20:23]
	v_mfma_f32_16x16x32_bf16 v[16:19], v[114:117], v[94:97], v[16:19]
	v_mfma_f32_16x16x32_bf16 v[12:15], v[102:105], v[98:101], v[12:15]
	v_mfma_f32_16x16x32_bf16 v[8:11], v[106:109], v[98:101], v[8:11]
	v_mfma_f32_16x16x32_bf16 v[4:7], v[110:113], v[98:101], v[4:7]
	v_mfma_f32_16x16x32_bf16 v[0:3], v[114:117], v[98:101], v[0:3]
	ds_read_b128 v[76:79], v80
	ds_read_b128 v[90:93], v80 offset:1024
	ds_read_b128 v[94:97], v80 offset:2048
	ds_read_b128 v[98:101], v80 offset:3072
	ds_read_b128 v[102:105], v81
	ds_read_b128 v[106:109], v81 offset:1024
	ds_read_b128 v[110:113], v81 offset:2048
	ds_read_b128 v[114:117], v81 offset:3072
	s_waitcnt lgkmcnt(0)
	s_nop 0
	v_mfma_f32_16x16x32_bf16 v[60:63], v[102:105], v[76:79], v[60:63]
	v_mfma_f32_16x16x32_bf16 v[56:59], v[106:109], v[76:79], v[56:59]
	v_mfma_f32_16x16x32_bf16 v[52:55], v[110:113], v[76:79], v[52:55]
	v_mfma_f32_16x16x32_bf16 v[48:51], v[114:117], v[76:79], v[48:51]
	v_mfma_f32_16x16x32_bf16 v[44:47], v[102:105], v[90:93], v[44:47]
	v_mfma_f32_16x16x32_bf16 v[40:43], v[106:109], v[90:93], v[40:43]
	v_mfma_f32_16x16x32_bf16 v[36:39], v[110:113], v[90:93], v[36:39]
	v_mfma_f32_16x16x32_bf16 v[32:35], v[114:117], v[90:93], v[32:35]
	v_mfma_f32_16x16x32_bf16 v[28:31], v[102:105], v[94:97], v[28:31]
	v_mfma_f32_16x16x32_bf16 v[24:27], v[106:109], v[94:97], v[24:27]
	v_mfma_f32_16x16x32_bf16 v[20:23], v[110:113], v[94:97], v[20:23]
	v_mfma_f32_16x16x32_bf16 v[16:19], v[114:117], v[94:97], v[16:19]
	v_mfma_f32_16x16x32_bf16 v[12:15], v[102:105], v[98:101], v[12:15]
	v_mfma_f32_16x16x32_bf16 v[8:11], v[106:109], v[98:101], v[8:11]
	v_mfma_f32_16x16x32_bf16 v[4:7], v[110:113], v[98:101], v[4:7]
	v_mfma_f32_16x16x32_bf16 v[0:3], v[114:117], v[98:101], v[0:3]
	s_cbranch_scc0 .LBB0_1577
	s_waitcnt vmcnt(4)
	s_waitcnt lgkmcnt(0)
	s_barrier
	ds_read_b128 v[64:67], v86 offset:32768
	ds_read_b128 v[76:79], v86 offset:33792
	ds_read_b128 v[90:93], v86 offset:34816
	ds_read_b128 v[94:97], v86 offset:35840
	ds_read_b128 v[98:101], v87 offset:32768
	ds_read_b128 v[102:105], v87 offset:33792
	ds_read_b128 v[106:109], v87 offset:34816
	ds_read_b128 v[110:113], v87 offset:35840
	s_waitcnt lgkmcnt(0)
	s_waitcnt vmcnt(0)
	s_waitcnt lgkmcnt(0)
	s_barrier
	v_mfma_f32_16x16x32_bf16 v[56:59], v[102:105], v[64:67], v[56:59]
	s_movk_i32 s16, 0xfff
	v_readlane_b32 s36, v241, 1
	v_mfma_f32_16x16x32_bf16 v[40:43], v[102:105], v[76:79], v[40:43]
	v_readlane_b32 s44, v241, 9
	v_readlane_b32 s45, v241, 10
	s_add_i32 s2, s2, s3
	v_mfma_f32_16x16x32_bf16 v[24:27], v[102:105], v[90:93], v[24:27]
	s_add_i32 s20, s20, s21
	v_readlane_b32 s37, v241, 2
	v_readlane_b32 s38, v241, 3
	v_mfma_f32_16x16x32_bf16 v[52:55], v[106:109], v[64:67], v[52:55]
	v_readlane_b32 s39, v241, 4
	v_readlane_b32 s40, v241, 5
	v_readlane_b32 s41, v241, 6
	v_mfma_f32_16x16x32_bf16 v[36:39], v[106:109], v[76:79], v[36:39]
	v_readlane_b32 s42, v241, 7
	v_readlane_b32 s43, v241, 8
	v_readlane_b32 s46, v241, 11
	v_mfma_f32_16x16x32_bf16 v[20:23], v[106:109], v[90:93], v[20:23]
	v_readlane_b32 s47, v241, 12
	v_readlane_b32 s48, v241, 13
	v_readlane_b32 s49, v241, 14
	v_mfma_f32_16x16x32_bf16 v[60:63], v[98:101], v[64:67], v[60:63]
	v_readlane_b32 s50, v241, 15
	v_readlane_b32 s51, v241, 16
	v_mfma_f32_16x16x32_bf16 v[48:51], v[110:113], v[64:67], v[48:51]
	v_mfma_f32_16x16x32_bf16 v[44:47], v[98:101], v[76:79], v[44:47]
	v_mfma_f32_16x16x32_bf16 v[32:35], v[110:113], v[76:79], v[32:35]
	v_mfma_f32_16x16x32_bf16 v[28:31], v[98:101], v[90:93], v[28:31]
	v_mfma_f32_16x16x32_bf16 v[16:19], v[110:113], v[90:93], v[16:19]
	v_mfma_f32_16x16x32_bf16 v[12:15], v[98:101], v[94:97], v[12:15]
	v_mfma_f32_16x16x32_bf16 v[8:11], v[102:105], v[94:97], v[8:11]
	v_mfma_f32_16x16x32_bf16 v[4:7], v[106:109], v[94:97], v[4:7]
	v_mfma_f32_16x16x32_bf16 v[0:3], v[110:113], v[94:97], v[0:3]
	ds_read_b128 v[64:67], v86 offset:49152
	ds_read_b128 v[76:79], v86 offset:50176
	ds_read_b128 v[90:93], v86 offset:51200
	ds_read_b128 v[94:97], v86 offset:52224
	ds_read_b128 v[98:101], v87 offset:49152
	ds_read_b128 v[102:105], v87 offset:50176
	ds_read_b128 v[106:109], v87 offset:51200
	ds_read_b128 v[110:113], v87 offset:52224
	s_waitcnt lgkmcnt(0)
	s_waitcnt lgkmcnt(0)
	s_barrier
	v_mfma_f32_16x16x32_bf16 v[118:121], v[102:105], v[64:67], v[56:59]
	v_mfma_f32_16x16x32_bf16 v[56:59], v[102:105], v[76:79], v[40:43]
	v_mfma_f32_16x16x32_bf16 v[40:43], v[102:105], v[90:93], v[24:27]
	s_nop 2
	v_add_u32_e32 v24, s31, v84
	v_mfma_f32_16x16x32_bf16 v[122:125], v[106:109], v[64:67], v[52:55]
	v_cmp_lt_i32_e32 vcc, s16, v24
	s_movk_i32 s16, 0x6000
	v_mfma_f32_16x16x32_bf16 v[52:55], v[106:109], v[76:79], v[36:39]
	v_mfma_f32_16x16x32_bf16 v[36:39], v[106:109], v[90:93], v[20:23]
	s_nop 2
	v_add_u32_e32 v21, 0xfffff000, v24
	v_lshrrev_b32_e32 v21, 12, v21
	v_add_u32_e32 v21, 1, v21
	v_or_b32_e32 v20, s33, v85
	v_cndmask_b32_e32 v21, 0, v21, vcc
	v_mad_u64_u32 v[22:23], s[16:17], v21, s16, v[74:75]
	v_ashrrev_i32_e32 v21, 31, v20
	v_mfma_f32_16x16x32_bf16 v[114:117], v[98:101], v[64:67], v[60:63]
	s_mov_b64 s[16:17], 0x5000
	v_mfma_f32_16x16x32_bf16 v[64:67], v[110:113], v[64:67], v[48:51]
	v_mfma_f32_16x16x32_bf16 v[60:63], v[98:101], v[76:79], v[44:47]
	v_mfma_f32_16x16x32_bf16 v[48:51], v[110:113], v[76:79], v[32:35]
	v_lshlrev_b64 v[76:77], 2, v[20:21]
	v_lshl_add_u64 v[20:21], v[22:23], 0, v[76:77]
	v_lshl_add_u64 v[20:21], v[20:21], 0, v[68:69]
	v_lshl_add_u64 v[22:23], v[20:21], 0, s[16:17]
	s_movk_i32 s16, 0x5000
	v_add_co_u32_e32 v20, vcc, s16, v20
	v_mfma_f32_16x16x32_bf16 v[44:47], v[98:101], v[90:93], v[28:31]
	s_nop 0
	v_addc_co_u32_e32 v21, vcc, 0, v21, vcc
	v_mfma_f32_16x16x32_bf16 v[16:19], v[110:113], v[90:93], v[16:19]
	v_or_b32_e32 v90, v24, v82
	v_or_b32_e32 v80, 32, v90
	v_or_b32_e32 v78, 48, v90
	v_mfma_f32_16x16x32_bf16 v[12:15], v[98:101], v[94:97], v[12:15]
	global_load_dwordx4 v[32:35], v[20:21], off
	global_load_dwordx4 v[28:31], v[22:23], off offset:64
	global_load_dwordx4 v[24:27], v[22:23], off offset:128
	s_nop 0
	global_load_dwordx4 v[20:23], v[22:23], off offset:192
	v_mfma_f32_16x16x32_bf16 v[8:11], v[102:105], v[94:97], v[8:11]
	v_mfma_f32_16x16x32_bf16 v[4:7], v[106:109], v[94:97], v[4:7]
	v_mfma_f32_16x16x32_bf16 v[0:3], v[110:113], v[94:97], v[0:3]
	v_or_b32_e32 v94, 16, v90
	s_nop 0
	v_mov_b32_e32 v190, v90
	v_ashrrev_i32_e32 v191, 31, v90
	v_lshlrev_b64 v[190:191], 12, v[190:191]
	v_lshl_add_u64 v[190:191], s[44:45], 0, v[190:191]
	v_lshl_add_u64 v[190:191], v[190:191], 0, v[76:77]
	v_lshl_add_u64 v[190:191], v[190:191], 0, v[68:69]
	v_mov_b32_e32 v192, v94
	v_ashrrev_i32_e32 v193, 31, v94
	v_lshlrev_b64 v[192:193], 12, v[192:193]
	v_lshl_add_u64 v[192:193], s[44:45], 0, v[192:193]
	v_lshl_add_u64 v[192:193], v[192:193], 0, v[76:77]
	v_lshl_add_u64 v[192:193], v[192:193], 0, v[68:69]
	v_mov_b32_e32 v194, v80
	v_ashrrev_i32_e32 v195, 31, v80
	v_lshlrev_b64 v[194:195], 12, v[194:195]
	v_lshl_add_u64 v[194:195], s[44:45], 0, v[194:195]
	v_lshl_add_u64 v[194:195], v[194:195], 0, v[76:77]
	v_lshl_add_u64 v[194:195], v[194:195], 0, v[68:69]
	v_mov_b32_e32 v196, v78
	v_ashrrev_i32_e32 v197, 31, v78
	v_lshlrev_b64 v[196:197], 12, v[196:197]
	v_lshl_add_u64 v[196:197], s[44:45], 0, v[196:197]
	v_lshl_add_u64 v[196:197], v[196:197], 0, v[76:77]
	v_lshl_add_u64 v[196:197], v[196:197], 0, v[68:69]
	global_load_dwordx4 v[126:129], v[190:191], off
	global_load_dwordx4 v[130:133], v[190:191], off offset:64
	global_load_dwordx4 v[134:137], v[190:191], off offset:128
	global_load_dwordx4 v[138:141], v[190:191], off offset:192
	global_load_dwordx4 v[142:145], v[192:193], off
	global_load_dwordx4 v[146:149], v[192:193], off offset:64
	global_load_dwordx4 v[150:153], v[192:193], off offset:128
	global_load_dwordx4 v[154:157], v[192:193], off offset:192
	global_load_dwordx4 v[158:161], v[194:195], off
	global_load_dwordx4 v[162:165], v[194:195], off offset:64
	global_load_dwordx4 v[166:169], v[194:195], off offset:128
	global_load_dwordx4 v[170:173], v[194:195], off offset:192
	global_load_dwordx4 v[174:177], v[196:197], off
	global_load_dwordx4 v[178:181], v[196:197], off offset:64
	global_load_dwordx4 v[182:185], v[196:197], off offset:128
	global_load_dwordx4 v[186:189], v[196:197], off offset:192
	s_waitcnt vmcnt(15)
	v_pk_mul_f32 v[126:127], v[126:127], s[14:15] op_sel_hi:[1,0]
	v_pk_mul_f32 v[128:129], v[128:129], s[14:15] op_sel_hi:[1,0]
	v_pk_fma_f32 v[126:127], v[114:115], v[32:33], v[126:127]
	v_pk_fma_f32 v[128:129], v[116:117], v[34:35], v[128:129]
	global_store_dwordx4 v[190:191], v[126:129], off
	s_waitcnt vmcnt(15)
	v_pk_mul_f32 v[130:131], v[130:131], s[14:15] op_sel_hi:[1,0]
	v_pk_mul_f32 v[132:133], v[132:133], s[14:15] op_sel_hi:[1,0]
	v_pk_fma_f32 v[130:131], v[118:119], v[28:29], v[130:131]
	v_pk_fma_f32 v[132:133], v[120:121], v[30:31], v[132:133]
	global_store_dwordx4 v[190:191], v[130:133], off offset:64
	s_waitcnt vmcnt(15)
	v_pk_mul_f32 v[134:135], v[134:135], s[14:15] op_sel_hi:[1,0]
	v_pk_mul_f32 v[136:137], v[136:137], s[14:15] op_sel_hi:[1,0]
	v_pk_fma_f32 v[134:135], v[122:123], v[24:25], v[134:135]
	v_pk_fma_f32 v[136:137], v[124:125], v[26:27], v[136:137]
	global_store_dwordx4 v[190:191], v[134:137], off offset:128
	s_waitcnt vmcnt(15)
	v_pk_mul_f32 v[138:139], v[138:139], s[14:15] op_sel_hi:[1,0]
	v_pk_fma_f32 v[64:65], v[64:65], v[20:21], v[138:139]
	v_pk_mul_f32 v[138:139], v[140:141], s[14:15] op_sel_hi:[1,0]
	v_pk_fma_f32 v[66:67], v[66:67], v[22:23], v[138:139]
	global_store_dwordx4 v[190:191], v[64:67], off offset:192
	s_waitcnt vmcnt(15)
	v_pk_mul_f32 v[142:143], v[142:143], s[14:15] op_sel_hi:[1,0]
	v_pk_fma_f32 v[60:61], v[60:61], v[32:33], v[142:143]
	v_pk_mul_f32 v[142:143], v[144:145], s[14:15] op_sel_hi:[1,0]
	v_pk_fma_f32 v[62:63], v[62:63], v[34:35], v[142:143]
	global_store_dwordx4 v[192:193], v[60:63], off
	s_waitcnt vmcnt(15)
	v_pk_mul_f32 v[146:147], v[146:147], s[14:15] op_sel_hi:[1,0]
	v_pk_fma_f32 v[56:57], v[56:57], v[28:29], v[146:147]
	v_pk_mul_f32 v[146:147], v[148:149], s[14:15] op_sel_hi:[1,0]
	v_pk_fma_f32 v[58:59], v[58:59], v[30:31], v[146:147]
	global_store_dwordx4 v[192:193], v[56:59], off offset:64
	s_waitcnt vmcnt(15)
	v_pk_mul_f32 v[150:151], v[150:151], s[14:15] op_sel_hi:[1,0]
	v_pk_fma_f32 v[52:53], v[52:53], v[24:25], v[150:151]
	v_pk_mul_f32 v[150:151], v[152:153], s[14:15] op_sel_hi:[1,0]
	v_pk_fma_f32 v[54:55], v[54:55], v[26:27], v[150:151]
	global_store_dwordx4 v[192:193], v[52:55], off offset:128
	s_waitcnt vmcnt(15)
	v_pk_mul_f32 v[154:155], v[154:155], s[14:15] op_sel_hi:[1,0]
	v_pk_fma_f32 v[48:49], v[48:49], v[20:21], v[154:155]
	v_pk_mul_f32 v[154:155], v[156:157], s[14:15] op_sel_hi:[1,0]
	v_pk_fma_f32 v[50:51], v[50:51], v[22:23], v[154:155]
	global_store_dwordx4 v[192:193], v[48:51], off offset:192
	s_waitcnt vmcnt(15)
	v_pk_mul_f32 v[158:159], v[158:159], s[14:15] op_sel_hi:[1,0]
	v_pk_fma_f32 v[44:45], v[44:45], v[32:33], v[158:159]
	v_pk_mul_f32 v[158:159], v[160:161], s[14:15] op_sel_hi:[1,0]
	v_pk_fma_f32 v[46:47], v[46:47], v[34:35], v[158:159]
	global_store_dwordx4 v[194:195], v[44:47], off
	s_waitcnt vmcnt(15)
	v_pk_mul_f32 v[162:163], v[162:163], s[14:15] op_sel_hi:[1,0]
	v_pk_fma_f32 v[40:41], v[40:41], v[28:29], v[162:163]
	v_pk_mul_f32 v[162:163], v[164:165], s[14:15] op_sel_hi:[1,0]
	v_pk_fma_f32 v[42:43], v[42:43], v[30:31], v[162:163]
	global_store_dwordx4 v[194:195], v[40:43], off offset:64
	s_waitcnt vmcnt(15)
	v_pk_mul_f32 v[166:167], v[166:167], s[14:15] op_sel_hi:[1,0]
	v_pk_fma_f32 v[36:37], v[36:37], v[24:25], v[166:167]
	v_pk_mul_f32 v[166:167], v[168:169], s[14:15] op_sel_hi:[1,0]
	v_pk_fma_f32 v[38:39], v[38:39], v[26:27], v[166:167]
	global_store_dwordx4 v[194:195], v[36:39], off offset:128
	s_waitcnt vmcnt(15)
	v_pk_mul_f32 v[170:171], v[170:171], s[14:15] op_sel_hi:[1,0]
	v_pk_fma_f32 v[16:17], v[16:17], v[20:21], v[170:171]
	v_pk_mul_f32 v[170:171], v[172:173], s[14:15] op_sel_hi:[1,0]
	v_pk_fma_f32 v[18:19], v[18:19], v[22:23], v[170:171]
	global_store_dwordx4 v[194:195], v[16:19], off offset:192
	s_waitcnt vmcnt(15)
	v_pk_mul_f32 v[174:175], v[174:175], s[14:15] op_sel_hi:[1,0]
	v_pk_fma_f32 v[12:13], v[12:13], v[32:33], v[174:175]
	v_pk_mul_f32 v[174:175], v[176:177], s[14:15] op_sel_hi:[1,0]
	v_pk_fma_f32 v[14:15], v[14:15], v[34:35], v[174:175]
	global_store_dwordx4 v[196:197], v[12:15], off
	s_waitcnt vmcnt(15)
	v_pk_mul_f32 v[178:179], v[178:179], s[14:15] op_sel_hi:[1,0]
	v_pk_fma_f32 v[8:9], v[8:9], v[28:29], v[178:179]
	v_pk_mul_f32 v[178:179], v[180:181], s[14:15] op_sel_hi:[1,0]
	v_pk_fma_f32 v[10:11], v[10:11], v[30:31], v[178:179]
	global_store_dwordx4 v[196:197], v[8:11], off offset:64
	s_waitcnt vmcnt(15)
	v_pk_mul_f32 v[182:183], v[182:183], s[14:15] op_sel_hi:[1,0]
	v_pk_fma_f32 v[4:5], v[4:5], v[24:25], v[182:183]
	v_pk_mul_f32 v[182:183], v[184:185], s[14:15] op_sel_hi:[1,0]
	v_pk_fma_f32 v[6:7], v[6:7], v[26:27], v[182:183]
	global_store_dwordx4 v[196:197], v[4:7], off offset:128
	s_waitcnt vmcnt(15)
	v_pk_mul_f32 v[186:187], v[186:187], s[14:15] op_sel_hi:[1,0]
	v_pk_fma_f32 v[0:1], v[0:1], v[20:21], v[186:187]
	v_pk_mul_f32 v[186:187], v[188:189], s[14:15] op_sel_hi:[1,0]
	s_add_i32 s15, s15, s30
	v_pk_fma_f32 v[2:3], v[2:3], v[22:23], v[186:187]
	s_cmpk_gt_i32 s2, 0x9f
	global_store_dwordx4 v[196:197], v[0:3], off offset:192
	s_cbranch_scc0 .LBB0_1576

.LBB0_2892:
	s_cmp_lt_u32 s46, 10
	s_cselect_b32 s52, s42, 0x500
	s_cselect_b32 s10, s57, s59
	s_cselect_b32 s49, s56, s58
	s_cselect_b32 s54, 0, 0xfffffe80
	v_mad_i64_i32 v[92:93], s[50:51], s52, v64, 0
	s_cselect_b32 s53, 0, -1
	v_mov_b32_e32 v90, s49
	v_mov_b32_e32 v91, s10
	s_add_u32 s50, s24, s54
	v_lshl_add_u64 v[90:91], v[92:93], 1, v[90:91]
	s_addc_u32 s51, s25, s53
	s_lshl_b32 s49, s47, 14
	v_lshl_add_u64 v[90:91], s[50:51], 1, v[90:91]
	s_waitcnt vmcnt(0)
	s_lshl_b32 s10, s52, 5
	s_add_i32 s49, s28, s49
	v_lshl_add_u64 v[120:121], v[90:91], 0, v[68:69]
	s_waitcnt lgkmcnt(0)
	s_barrier
	v_lshl_add_u64 v[90:91], v[120:121], 0, s[12:13]
	v_lshl_add_u64 v[122:123], v[120:121], 0, s[10:11]
	s_mov_b32 m0, s49
	v_lshl_add_u64 v[118:119], v[66:67], 0, s[26:27]
	global_load_lds_dwordx4 v[90:91], off
	v_lshl_add_u64 v[90:91], v[122:123], 0, s[12:13]
	s_add_i32 m0, s49, 0x400
	v_lshl_add_u64 v[78:79], v[118:119], 0, s[12:13]
	global_load_lds_dwordx4 v[90:91], off
	s_add_i32 m0, s49, 0x2000
	s_lshl_b32 s52, s48, 14
	global_load_lds_dwordx4 v[78:79], off
	s_add_i32 m0, s49, 0x2400
	s_add_i32 s10, s48, 1
	s_cmp_lg_u32 s48, 3
	s_cselect_b32 s10, s10, 0
	s_add_i32 s48, s47, 1
	v_lshl_add_u64 v[80:81], v[118:119], 0, s[14:15]
	s_cmp_lg_u32 s47, 3
	global_load_lds_dwordx4 v[80:81], off
	s_cselect_b32 s47, s48, 0
	v_add_u32_e32 v65, s52, v86
	v_or_b32_e32 v124, s52, v87
	ds_read_b128 v[78:81], v65
	ds_read_b128 v[90:93], v65 offset:1024
	ds_read_b128 v[94:97], v65 offset:2048
	ds_read_b128 v[98:101], v65 offset:3072
	ds_read_b128 v[102:105], v124
	ds_read_b128 v[106:109], v124 offset:1024
	ds_read_b128 v[110:113], v124 offset:2048
	ds_read_b128 v[114:117], v124 offset:3072
	s_waitcnt lgkmcnt(0)
	s_lshl_b32 s48, s47, 14
	s_add_i32 s48, s28, s48
	v_mfma_f32_16x16x32_bf16 v[44:47], v[102:105], v[90:93], v[44:47]
	v_mfma_f32_16x16x32_bf16 v[40:43], v[106:109], v[90:93], v[40:43]
	s_mov_b32 m0, s48
	s_add_i32 s46, s46, 2
	v_mfma_f32_16x16x32_bf16 v[36:39], v[110:113], v[90:93], v[36:39]
	v_mfma_f32_16x16x32_bf16 v[32:35], v[114:117], v[90:93], v[32:35]
	v_lshl_add_u64 v[90:91], v[120:121], 0, s[16:17]
	v_lshl_add_u64 v[92:93], v[122:123], 0, s[16:17]
	global_load_lds_dwordx4 v[90:91], off
	s_add_i32 m0, s48, 0x400
	v_mfma_f32_16x16x32_bf16 v[60:63], v[102:105], v[78:81], v[60:63]
	global_load_lds_dwordx4 v[92:93], off
	s_add_i32 m0, s48, 0x2000
	v_mfma_f32_16x16x32_bf16 v[56:59], v[106:109], v[78:81], v[56:59]
	v_mfma_f32_16x16x32_bf16 v[52:55], v[110:113], v[78:81], v[52:55]
	v_mfma_f32_16x16x32_bf16 v[48:51], v[114:117], v[78:81], v[48:51]
	v_lshl_add_u64 v[78:79], v[118:119], 0, s[16:17]
	v_lshl_add_u64 v[80:81], v[118:119], 0, s[18:19]
	global_load_lds_dwordx4 v[78:79], off
	s_add_i32 m0, s48, 0x2400
	s_lshl_b32 s48, s10, 14
	global_load_lds_dwordx4 v[80:81], off
	v_add_u32_e32 v65, s48, v86
	v_or_b32_e32 v118, s48, v87
	s_add_i32 s48, s10, 1
	v_mfma_f32_16x16x32_bf16 v[28:31], v[102:105], v[94:97], v[28:31]
	s_cmp_lg_u32 s10, 3
	s_cselect_b32 s48, s48, 0
	s_add_i32 s10, s47, 1
	v_mfma_f32_16x16x32_bf16 v[20:23], v[106:109], v[94:97], v[20:23]
	s_cmp_lg_u32 s47, 3
	s_cselect_b32 s47, s10, 0
	s_add_u32 s26, s26, 0x80
	v_mfma_f32_16x16x32_bf16 v[16:19], v[110:113], v[94:97], v[16:19]
	s_addc_u32 s27, s27, 0
	s_add_u32 s24, s24, 64
	s_addc_u32 s25, s25, 0
	v_mfma_f32_16x16x32_bf16 v[12:15], v[114:117], v[94:97], v[12:15]
	s_cmpk_eq_i32 s26, 0x780
	v_mfma_f32_16x16x32_bf16 v[8:11], v[102:105], v[98:101], v[8:11]
	v_mfma_f32_16x16x32_bf16 v[4:7], v[106:109], v[98:101], v[4:7]
	v_mfma_f32_16x16x32_bf16 v[0:3], v[110:113], v[98:101], v[0:3]
	v_mfma_f32_16x16x32_bf16 v[24:27], v[114:117], v[98:101], v[24:27]
	ds_read_b128 v[78:81], v65
	ds_read_b128 v[90:93], v65 offset:1024
	ds_read_b128 v[94:97], v65 offset:2048
	ds_read_b128 v[98:101], v65 offset:3072
	ds_read_b128 v[102:105], v118
	ds_read_b128 v[106:109], v118 offset:1024
	ds_read_b128 v[110:113], v118 offset:2048
	ds_read_b128 v[114:117], v118 offset:3072
	s_waitcnt lgkmcnt(0)
	s_nop 0
	v_mfma_f32_16x16x32_bf16 v[60:63], v[102:105], v[78:81], v[60:63]
	v_mfma_f32_16x16x32_bf16 v[56:59], v[106:109], v[78:81], v[56:59]
	v_mfma_f32_16x16x32_bf16 v[52:55], v[110:113], v[78:81], v[52:55]
	v_mfma_f32_16x16x32_bf16 v[48:51], v[114:117], v[78:81], v[48:51]
	v_mfma_f32_16x16x32_bf16 v[44:47], v[102:105], v[90:93], v[44:47]
	v_mfma_f32_16x16x32_bf16 v[40:43], v[106:109], v[90:93], v[40:43]
	v_mfma_f32_16x16x32_bf16 v[36:39], v[110:113], v[90:93], v[36:39]
	v_mfma_f32_16x16x32_bf16 v[32:35], v[114:117], v[90:93], v[32:35]
	v_mfma_f32_16x16x32_bf16 v[28:31], v[102:105], v[94:97], v[28:31]
	v_mfma_f32_16x16x32_bf16 v[20:23], v[106:109], v[94:97], v[20:23]
	v_mfma_f32_16x16x32_bf16 v[16:19], v[110:113], v[94:97], v[16:19]
	v_mfma_f32_16x16x32_bf16 v[12:15], v[114:117], v[94:97], v[12:15]
	v_mfma_f32_16x16x32_bf16 v[8:11], v[102:105], v[98:101], v[8:11]
	v_mfma_f32_16x16x32_bf16 v[4:7], v[106:109], v[98:101], v[4:7]
	v_mfma_f32_16x16x32_bf16 v[0:3], v[110:113], v[98:101], v[0:3]
	v_mfma_f32_16x16x32_bf16 v[24:27], v[114:117], v[98:101], v[24:27]
	s_cbranch_scc0 .LBB0_2892
	s_waitcnt vmcnt(4)
	s_waitcnt lgkmcnt(0)
	s_barrier
	ds_read_b128 v[64:67], v86 offset:32768
	ds_read_b128 v[78:81], v86 offset:33792
	ds_read_b128 v[90:93], v86 offset:34816
	ds_read_b128 v[94:97], v86 offset:35840
	ds_read_b128 v[98:101], v87 offset:32768
	ds_read_b128 v[102:105], v87 offset:33792
	ds_read_b128 v[106:109], v87 offset:34816
	ds_read_b128 v[110:113], v87 offset:35840
	s_waitcnt lgkmcnt(0)
	s_waitcnt vmcnt(0)
	s_waitcnt lgkmcnt(0)
	s_barrier
	v_mfma_f32_16x16x32_bf16 v[158:161], v[102:105], v[90:93], v[20:23]
	s_add_i32 s2, s2, s3
	s_add_i32 s31, s31, s33
	v_mfma_f32_16x16x32_bf16 v[114:117], v[98:101], v[64:67], v[60:63]
	v_add_u32_e32 v22, s44, v84
	v_or_b32_e32 v20, s45, v85
	v_cmp_lt_i32_e32 vcc, s43, v22
	v_mfma_f32_16x16x32_bf16 v[118:121], v[102:105], v[64:67], v[56:59]
	v_ashrrev_i32_e32 v21, 31, v20
	v_readlane_b32 s44, v241, 1
	v_readlane_b32 s52, v241, 9
	v_mfma_f32_16x16x32_bf16 v[122:125], v[106:109], v[64:67], v[52:55]
	v_readlane_b32 s53, v241, 10
	s_cmpk_gt_i32 s2, 0x9f
	v_readlane_b32 s45, v241, 2
	v_mfma_f32_16x16x32_bf16 v[126:129], v[110:113], v[64:67], v[48:51]
	v_readlane_b32 s46, v241, 3
	v_readlane_b32 s47, v241, 4
	v_readlane_b32 s48, v241, 5
	v_mfma_f32_16x16x32_bf16 v[64:67], v[106:109], v[90:93], v[16:19]
	v_readlane_b32 s49, v241, 6
	v_readlane_b32 s50, v241, 7
	v_readlane_b32 s51, v241, 8
	v_add_u32_e32 v16, 0xfffff000, v22
	v_lshrrev_b32_e32 v16, 12, v16
	v_add_u32_e32 v16, 6, v16
	v_mfma_f32_16x16x32_bf16 v[60:63], v[110:113], v[90:93], v[12:15]
	v_readlane_b32 s54, v241, 11
	v_readlane_b32 s55, v241, 12
	v_readlane_b32 s56, v241, 13
	v_cndmask_b32_e32 v12, 5, v16, vcc
	v_mfma_f32_16x16x32_bf16 v[130:133], v[98:101], v[78:81], v[44:47]
	v_mad_u64_u32 v[12:13], s[24:25], v12, s30, v[74:75]
	v_readlane_b32 s57, v241, 14
	v_mfma_f32_16x16x32_bf16 v[134:137], v[102:105], v[78:81], v[40:43]
	v_readlane_b32 s58, v241, 15
	v_readlane_b32 s59, v241, 16
	v_mfma_f32_16x16x32_bf16 v[138:141], v[106:109], v[78:81], v[36:39]
	v_mfma_f32_16x16x32_bf16 v[142:145], v[110:113], v[78:81], v[32:35]
	v_lshlrev_b64 v[78:79], 2, v[20:21]
	v_mfma_f32_16x16x32_bf16 v[52:55], v[98:101], v[94:97], v[8:11]
	s_nop 2
	v_lshl_add_u64 v[8:9], v[12:13], 0, v[78:79]
	v_lshl_add_u64 v[8:9], v[8:9], 0, v[76:77]
	v_mfma_f32_16x16x32_bf16 v[146:149], v[98:101], v[90:93], v[28:31]
	ds_read_b128 v[150:153], v86 offset:49152
	ds_read_b128 v[154:157], v86 offset:50176
	ds_read_b128 v[56:59], v86 offset:51200
	ds_read_b128 v[28:31], v86 offset:52224
	ds_read_b128 v[44:47], v87 offset:49152
	ds_read_b128 v[40:43], v87 offset:50176
	ds_read_b128 v[36:39], v87 offset:51200
	ds_read_b128 v[32:35], v87 offset:52224
	s_waitcnt lgkmcnt(0)
	v_add_co_u32_e32 v14, vcc, s29, v8
	s_waitcnt lgkmcnt(0)
	s_barrier
	v_lshl_add_u64 v[12:13], v[8:9], 0, s[20:21]
	v_or_b32_e32 v98, v22, v82
	v_addc_co_u32_e32 v15, vcc, 0, v9, vcc
	v_mfma_f32_16x16x32_bf16 v[20:23], v[106:109], v[94:97], v[0:3]
	v_or_b32_e32 v162, 16, v98
	v_or_b32_e32 v164, 32, v98
	v_or_b32_e32 v80, 48, v98
	global_load_dwordx4 v[0:3], v[12:13], off offset:64
	global_load_dwordx4 v[8:11], v[12:13], off offset:128
	global_load_dwordx4 v[16:19], v[14:15], off
	s_nop 0
	global_load_dwordx4 v[12:15], v[12:13], off offset:192
	v_mfma_f32_16x16x32_bf16 v[48:51], v[102:105], v[94:97], v[4:7]
	v_mov_b32_e32 v236, v98
	v_ashrrev_i32_e32 v237, 31, v98
	v_lshlrev_b64 v[236:237], 12, v[236:237]
	v_lshl_add_u64 v[236:237], s[52:53], 0, v[236:237]
	v_lshl_add_u64 v[236:237], v[236:237], 0, v[78:79]
	v_lshl_add_u64 v[236:237], v[236:237], 0, v[76:77]
	v_mov_b32_e32 v238, v162
	v_ashrrev_i32_e32 v239, 31, v162
	v_lshlrev_b64 v[238:239], 12, v[238:239]
	v_lshl_add_u64 v[238:239], s[52:53], 0, v[238:239]
	v_lshl_add_u64 v[238:239], v[238:239], 0, v[78:79]
	v_lshl_add_u64 v[238:239], v[238:239], 0, v[76:77]
	v_mov_b32_e32 v242, v164
	v_ashrrev_i32_e32 v243, 31, v164
	v_lshlrev_b64 v[242:243], 12, v[242:243]
	v_lshl_add_u64 v[242:243], s[52:53], 0, v[242:243]
	v_lshl_add_u64 v[242:243], v[242:243], 0, v[78:79]
	v_lshl_add_u64 v[242:243], v[242:243], 0, v[76:77]
	v_mov_b32_e32 v244, v80
	v_ashrrev_i32_e32 v245, 31, v80
	v_lshlrev_b64 v[244:245], 12, v[244:245]
	v_lshl_add_u64 v[244:245], s[52:53], 0, v[244:245]
	v_lshl_add_u64 v[244:245], v[244:245], 0, v[78:79]
	v_lshl_add_u64 v[244:245], v[244:245], 0, v[76:77]
	global_load_dwordx4 v[168:171], v[236:237], off
	global_load_dwordx4 v[172:175], v[236:237], off offset:64
	global_load_dwordx4 v[176:179], v[236:237], off offset:128
	global_load_dwordx4 v[180:183], v[236:237], off offset:192
	global_load_dwordx4 v[184:187], v[238:239], off
	global_load_dwordx4 v[188:191], v[238:239], off offset:64
	global_load_dwordx4 v[192:195], v[238:239], off offset:128
	global_load_dwordx4 v[196:199], v[238:239], off offset:192
	global_load_dwordx4 v[200:203], v[242:243], off
	global_load_dwordx4 v[204:207], v[242:243], off offset:64
	global_load_dwordx4 v[208:211], v[242:243], off offset:128
	global_load_dwordx4 v[212:215], v[242:243], off offset:192
	global_load_dwordx4 v[216:219], v[244:245], off
	global_load_dwordx4 v[220:223], v[244:245], off offset:64
	global_load_dwordx4 v[228:231], v[244:245], off offset:128
	global_load_dwordx4 v[232:235], v[244:245], off offset:192
	v_mfma_f32_16x16x32_bf16 v[4:7], v[110:113], v[94:97], v[24:27]
	v_mfma_f32_16x16x32_bf16 v[90:93], v[40:43], v[150:153], v[118:121]
	s_waitcnt vmcnt(15)
	v_pk_mul_f32 v[168:169], v[168:169], s[22:23] op_sel_hi:[1,0]
	v_mfma_f32_16x16x32_bf16 v[24:27], v[44:47], v[150:153], v[114:117]
	v_mul_f32_e64 v170, v170, s22
	v_mul_f32_e64 v171, v171, s22
	s_waitcnt vmcnt(14)
	v_pk_mul_f32 v[172:173], v[172:173], s[22:23] op_sel_hi:[1,0]
	v_pk_mul_f32 v[174:175], v[174:175], s[22:23] op_sel_hi:[1,0]
	v_mfma_f32_16x16x32_bf16 v[94:97], v[36:39], v[150:153], v[122:125]
	s_waitcnt vmcnt(13)
	v_mul_f32_e64 v176, v176, s22
	v_mul_f32_e64 v177, v177, s22
	v_pk_mul_f32 v[178:179], v[178:179], s[22:23] op_sel_hi:[1,0]
	v_pk_fma_f32 v[24:25], v[24:25], v[16:17], v[168:169]
	v_mfma_f32_16x16x32_bf16 v[102:105], v[32:35], v[150:153], v[126:129]
	v_fma_f32 v26, v26, v18, v170
	v_fma_f32 v27, v27, v19, v171
	v_pk_fma_f32 v[90:91], v[90:91], v[0:1], v[172:173]
	v_pk_fma_f32 v[92:93], v[92:93], v[2:3], v[174:175]
	v_pk_fma_f32 v[94:95], v[94:95], v[8:9], v[176:177]
	v_pk_fma_f32 v[96:97], v[96:97], v[10:11], v[178:179]
	v_mfma_f32_16x16x32_bf16 v[114:117], v[44:47], v[154:157], v[130:133]
	s_waitcnt vmcnt(12)
	v_pk_mul_f32 v[180:181], v[180:181], s[22:23] op_sel_hi:[1,0]
	v_pk_mul_f32 v[182:183], v[182:183], s[22:23] op_sel_hi:[1,0]
	v_pk_fma_f32 v[168:169], v[102:103], v[12:13], v[180:181]
	v_pk_fma_f32 v[170:171], v[104:105], v[14:15], v[182:183]
	global_store_dwordx4 v[236:237], v[24:27], off
	global_store_dwordx4 v[236:237], v[90:93], off offset:64
	global_store_dwordx4 v[236:237], v[94:97], off offset:128
	global_store_dwordx4 v[236:237], v[168:171], off offset:192
	v_mfma_f32_16x16x32_bf16 v[122:125], v[40:43], v[154:157], v[134:137]
	v_mfma_f32_16x16x32_bf16 v[90:93], v[36:39], v[154:157], v[138:141]
	s_waitcnt vmcnt(15)
	v_pk_mul_f32 v[184:185], v[184:185], s[22:23] op_sel_hi:[1,0]
	v_mfma_f32_16x16x32_bf16 v[102:105], v[32:35], v[154:157], v[142:145]
	v_mul_f32_e64 v186, v186, s22
	v_mul_f32_e64 v187, v187, s22
	s_waitcnt vmcnt(14)
	v_pk_mul_f32 v[188:189], v[188:189], s[22:23] op_sel_hi:[1,0]
	v_pk_mul_f32 v[190:191], v[190:191], s[22:23] op_sel_hi:[1,0]
	s_waitcnt vmcnt(13)
	v_pk_mul_f32 v[192:193], v[192:193], s[22:23] op_sel_hi:[1,0]
	v_pk_mul_f32 v[194:195], v[194:195], s[22:23] op_sel_hi:[1,0]
	s_waitcnt vmcnt(12)
	v_pk_mul_f32 v[196:197], v[196:197], s[22:23] op_sel_hi:[1,0]
	v_pk_mul_f32 v[198:199], v[198:199], s[22:23] op_sel_hi:[1,0]
	v_pk_fma_f32 v[184:185], v[114:115], v[16:17], v[184:185]
	v_pk_fma_f32 v[186:187], v[116:117], v[18:19], v[186:187]
	v_pk_fma_f32 v[188:189], v[122:123], v[0:1], v[188:189]
	v_pk_fma_f32 v[190:191], v[124:125], v[2:3], v[190:191]
	v_pk_fma_f32 v[90:91], v[90:91], v[8:9], v[192:193]
	v_pk_fma_f32 v[92:93], v[92:93], v[10:11], v[194:195]
	v_pk_fma_f32 v[192:193], v[102:103], v[12:13], v[196:197]
	v_pk_fma_f32 v[194:195], v[104:105], v[14:15], v[198:199]
	global_store_dwordx4 v[238:239], v[184:187], off
	global_store_dwordx4 v[238:239], v[188:191], off offset:64
	global_store_dwordx4 v[238:239], v[90:93], off offset:128
	global_store_dwordx4 v[238:239], v[192:195], off offset:192
	v_mfma_f32_16x16x32_bf16 v[176:179], v[44:47], v[56:59], v[146:149]
	v_mfma_f32_16x16x32_bf16 v[90:93], v[40:43], v[56:59], v[158:161]
	s_waitcnt vmcnt(15)
	v_pk_mul_f32 v[200:201], v[200:201], s[22:23] op_sel_hi:[1,0]
	v_mfma_f32_16x16x32_bf16 v[64:67], v[36:39], v[56:59], v[64:67]
	v_mul_f32_e64 v202, v202, s22
	v_mul_f32_e64 v203, v203, s22
	s_nop 1
	v_pk_fma_f32 v[200:201], v[176:177], v[16:17], v[200:201]
	s_nop 0
	v_pk_fma_f32 v[202:203], v[178:179], v[18:19], v[202:203]
	v_mfma_f32_16x16x32_bf16 v[56:59], v[32:35], v[56:59], v[60:63]
	s_waitcnt vmcnt(14)
	v_mul_f32_e64 v60, v204, s22
	v_mul_f32_e64 v61, v205, s22
	v_pk_mul_f32 v[62:63], v[206:207], s[22:23] op_sel_hi:[1,0]
	s_waitcnt vmcnt(13)
	v_pk_mul_f32 v[204:205], v[208:209], s[22:23] op_sel_hi:[1,0]
	v_pk_mul_f32 v[206:207], v[210:211], s[22:23] op_sel_hi:[1,0]
	s_waitcnt vmcnt(12)
	v_pk_mul_f32 v[208:209], v[212:213], s[22:23] op_sel_hi:[1,0]
	v_pk_mul_f32 v[210:211], v[214:215], s[22:23] op_sel_hi:[1,0]
	v_pk_fma_f32 v[60:61], v[90:91], v[0:1], v[60:61]
	v_pk_fma_f32 v[62:63], v[92:93], v[2:3], v[62:63]
	v_pk_fma_f32 v[64:65], v[64:65], v[8:9], v[204:205]
	v_pk_fma_f32 v[66:67], v[66:67], v[10:11], v[206:207]
	v_pk_fma_f32 v[56:57], v[56:57], v[12:13], v[208:209]
	v_pk_fma_f32 v[58:59], v[58:59], v[14:15], v[210:211]
	global_store_dwordx4 v[242:243], v[200:203], off
	global_store_dwordx4 v[242:243], v[60:63], off offset:64
	global_store_dwordx4 v[242:243], v[64:67], off offset:128
	global_store_dwordx4 v[242:243], v[56:59], off offset:192
	v_mfma_f32_16x16x32_bf16 v[44:47], v[44:47], v[28:31], v[52:55]
	v_mfma_f32_16x16x32_bf16 v[40:43], v[40:43], v[28:31], v[48:51]
	s_waitcnt vmcnt(15)
	v_pk_mul_f32 v[216:217], v[216:217], s[22:23] op_sel_hi:[1,0]
	v_mfma_f32_16x16x32_bf16 v[20:23], v[36:39], v[28:31], v[20:23]
	v_mul_f32_e64 v218, v218, s22
	v_mul_f32_e64 v219, v219, s22
	s_nop 1
	v_pk_fma_f32 v[16:17], v[44:45], v[16:17], v[216:217]
	s_nop 0
	v_pk_fma_f32 v[18:19], v[46:47], v[18:19], v[218:219]
	v_mfma_f32_16x16x32_bf16 v[4:7], v[32:35], v[28:31], v[4:7]
	s_waitcnt vmcnt(14)
	v_mul_f32_e64 v28, v220, s22
	v_mul_f32_e64 v29, v221, s22
	v_pk_mul_f32 v[30:31], v[222:223], s[22:23] op_sel_hi:[1,0]
	s_waitcnt vmcnt(13)
	v_pk_mul_f32 v[32:33], v[228:229], s[22:23] op_sel_hi:[1,0]
	v_pk_mul_f32 v[34:35], v[230:231], s[22:23] op_sel_hi:[1,0]
	v_pk_fma_f32 v[0:1], v[40:41], v[0:1], v[28:29]
	v_pk_fma_f32 v[2:3], v[42:43], v[2:3], v[30:31]
	v_pk_fma_f32 v[8:9], v[20:21], v[8:9], v[32:33]
	v_pk_fma_f32 v[10:11], v[22:23], v[10:11], v[34:35]
	s_waitcnt vmcnt(12)
	v_pk_mul_f32 v[36:37], v[232:233], s[22:23] op_sel_hi:[1,0]
	v_pk_mul_f32 v[38:39], v[234:235], s[22:23] op_sel_hi:[1,0]
	v_pk_fma_f32 v[4:5], v[4:5], v[12:13], v[36:37]
	v_pk_fma_f32 v[6:7], v[6:7], v[14:15], v[38:39]
	global_store_dwordx4 v[244:245], v[16:19], off
	global_store_dwordx4 v[244:245], v[0:3], off offset:64
	global_store_dwordx4 v[244:245], v[8:11], off offset:128
	global_store_dwordx4 v[244:245], v[4:7], off offset:192
	s_cbranch_scc0 .LBB0_2891

.LBB0_3063:
	s_lshl_b32 s41, s39, 14
	s_waitcnt vmcnt(0)
	v_lshl_add_u64 v[116:117], v[74:75], 0, s[18:19]
	s_add_i32 s41, s21, s41
	s_waitcnt lgkmcnt(0)
	s_barrier
	v_lshl_add_u64 v[84:85], v[116:117], 0, s[6:7]
	s_mov_b32 m0, s41
	v_lshl_add_u64 v[118:119], v[72:73], 0, s[18:19]
	v_lshl_add_u64 v[86:87], v[116:117], 0, s[8:9]
	global_load_lds_dwordx4 v[84:85], off
	s_add_i32 m0, s41, 0x400
	v_lshl_add_u64 v[88:89], v[118:119], 0, s[6:7]
	global_load_lds_dwordx4 v[86:87], off
	s_add_i32 m0, s41, 0x2000
	s_lshl_b32 s42, s40, 14
	global_load_lds_dwordx4 v[88:89], off
	s_add_i32 m0, s41, 0x2400
	s_add_i32 s41, s40, 1
	s_cmp_lg_u32 s40, 3
	s_cselect_b32 s40, s41, 0
	s_add_i32 s41, s39, 1
	v_lshl_add_u64 v[90:91], v[118:119], 0, s[8:9]
	s_cmp_lg_u32 s39, 3
	global_load_lds_dwordx4 v[90:91], off
	s_cselect_b32 s39, s41, 0
	v_add_u32_e32 v120, s42, v80
	v_or_b32_e32 v121, s42, v81
	ds_read_b128 v[84:87], v120
	ds_read_b128 v[88:91], v120 offset:1024
	ds_read_b128 v[92:95], v120 offset:2048
	ds_read_b128 v[96:99], v120 offset:3072
	ds_read_b128 v[100:103], v121
	ds_read_b128 v[104:107], v121 offset:1024
	ds_read_b128 v[108:111], v121 offset:2048
	ds_read_b128 v[112:115], v121 offset:3072
	s_waitcnt lgkmcnt(0)
	s_lshl_b32 s41, s39, 14
	s_add_i32 s41, s21, s41
	v_mfma_f32_16x16x32_bf16 v[60:63], v[100:103], v[84:87], v[60:63]
	v_mfma_f32_16x16x32_bf16 v[56:59], v[104:107], v[84:87], v[56:59]
	s_mov_b32 m0, s41
	v_mfma_f32_16x16x32_bf16 v[52:55], v[108:111], v[84:87], v[52:55]
	v_mfma_f32_16x16x32_bf16 v[48:51], v[112:115], v[84:87], v[48:51]
	v_lshl_add_u64 v[84:85], v[116:117], 0, s[10:11]
	v_lshl_add_u64 v[86:87], v[116:117], 0, s[12:13]
	global_load_lds_dwordx4 v[84:85], off
	s_add_i32 m0, s41, 0x400
	v_mfma_f32_16x16x32_bf16 v[44:47], v[100:103], v[88:91], v[44:47]
	global_load_lds_dwordx4 v[86:87], off
	s_add_i32 m0, s41, 0x2000
	v_mfma_f32_16x16x32_bf16 v[40:43], v[104:107], v[88:91], v[40:43]
	v_mfma_f32_16x16x32_bf16 v[36:39], v[108:111], v[88:91], v[36:39]
	v_mfma_f32_16x16x32_bf16 v[32:35], v[112:115], v[88:91], v[32:35]
	v_lshl_add_u64 v[88:89], v[118:119], 0, s[10:11]
	v_lshl_add_u64 v[90:91], v[118:119], 0, s[12:13]
	global_load_lds_dwordx4 v[88:89], off
	s_add_i32 m0, s41, 0x2400
	v_mfma_f32_16x16x32_bf16 v[28:31], v[100:103], v[92:95], v[28:31]
	global_load_lds_dwordx4 v[90:91], off
	s_lshl_b32 s41, s40, 14
	v_mfma_f32_16x16x32_bf16 v[24:27], v[104:107], v[92:95], v[24:27]
	v_add_u32_e32 v116, s41, v80
	v_or_b32_e32 v117, s41, v81
	s_add_i32 s41, s40, 1
	v_mfma_f32_16x16x32_bf16 v[16:19], v[108:111], v[92:95], v[16:19]
	s_cmp_lg_u32 s40, 3
	s_cselect_b32 s40, s41, 0
	s_add_i32 s41, s39, 1
	v_mfma_f32_16x16x32_bf16 v[12:15], v[112:115], v[92:95], v[12:15]
	s_cmp_lg_u32 s39, 3
	s_cselect_b32 s39, s41, 0
	s_add_u32 s18, s18, 0x80
	v_mfma_f32_16x16x32_bf16 v[8:11], v[100:103], v[96:99], v[8:11]
	s_addc_u32 s19, s19, 0
	s_cmpk_eq_i32 s18, 0x1580
	v_mfma_f32_16x16x32_bf16 v[4:7], v[104:107], v[96:99], v[4:7]
	v_mfma_f32_16x16x32_bf16 v[0:3], v[108:111], v[96:99], v[0:3]
	v_mfma_f32_16x16x32_bf16 v[20:23], v[112:115], v[96:99], v[20:23]
	ds_read_b128 v[84:87], v116
	ds_read_b128 v[88:91], v116 offset:1024
	ds_read_b128 v[92:95], v116 offset:2048
	ds_read_b128 v[96:99], v116 offset:3072
	ds_read_b128 v[100:103], v117
	ds_read_b128 v[104:107], v117 offset:1024
	ds_read_b128 v[108:111], v117 offset:2048
	ds_read_b128 v[112:115], v117 offset:3072
	s_waitcnt lgkmcnt(0)
	s_nop 0
	v_mfma_f32_16x16x32_bf16 v[60:63], v[100:103], v[84:87], v[60:63]
	v_mfma_f32_16x16x32_bf16 v[56:59], v[104:107], v[84:87], v[56:59]
	v_mfma_f32_16x16x32_bf16 v[52:55], v[108:111], v[84:87], v[52:55]
	v_mfma_f32_16x16x32_bf16 v[48:51], v[112:115], v[84:87], v[48:51]
	v_mfma_f32_16x16x32_bf16 v[44:47], v[100:103], v[88:91], v[44:47]
	v_mfma_f32_16x16x32_bf16 v[40:43], v[104:107], v[88:91], v[40:43]
	v_mfma_f32_16x16x32_bf16 v[36:39], v[108:111], v[88:91], v[36:39]
	v_mfma_f32_16x16x32_bf16 v[32:35], v[112:115], v[88:91], v[32:35]
	v_mfma_f32_16x16x32_bf16 v[28:31], v[100:103], v[92:95], v[28:31]
	v_mfma_f32_16x16x32_bf16 v[24:27], v[104:107], v[92:95], v[24:27]
	v_mfma_f32_16x16x32_bf16 v[16:19], v[108:111], v[92:95], v[16:19]
	v_mfma_f32_16x16x32_bf16 v[12:15], v[112:115], v[92:95], v[12:15]
	v_mfma_f32_16x16x32_bf16 v[8:11], v[100:103], v[96:99], v[8:11]
	v_mfma_f32_16x16x32_bf16 v[4:7], v[104:107], v[96:99], v[4:7]
	v_mfma_f32_16x16x32_bf16 v[0:3], v[108:111], v[96:99], v[0:3]
	v_mfma_f32_16x16x32_bf16 v[20:23], v[112:115], v[96:99], v[20:23]
	s_cbranch_scc0 .LBB0_3063
	s_waitcnt vmcnt(4)
	s_waitcnt lgkmcnt(0)
	s_barrier
	ds_read_b128 v[72:75], v80 offset:32768
	ds_read_b128 v[84:87], v80 offset:33792
	ds_read_b128 v[88:91], v80 offset:34816
	ds_read_b128 v[92:95], v80 offset:35840
	ds_read_b128 v[96:99], v81 offset:32768
	ds_read_b128 v[100:103], v81 offset:33792
	ds_read_b128 v[104:107], v81 offset:34816
	ds_read_b128 v[108:111], v81 offset:35840
	s_waitcnt lgkmcnt(0)
	s_waitcnt vmcnt(0)
	s_waitcnt lgkmcnt(0)
	s_barrier
	v_mfma_f32_16x16x32_bf16 v[112:115], v[96:99], v[72:75], v[60:63]
	v_readlane_b32 s40, v241, 1
	v_readlane_b32 s48, v241, 9
	v_mfma_f32_16x16x32_bf16 v[116:119], v[100:103], v[72:75], v[56:59]
	v_readlane_b32 s49, v241, 10
	s_add_i32 s2, s2, s3
	s_add_i32 s22, s22, s23
	v_mfma_f32_16x16x32_bf16 v[120:123], v[104:107], v[72:75], v[52:55]
	v_readlane_b32 s41, v241, 2
	v_readlane_b32 s42, v241, 3
	v_readlane_b32 s43, v241, 4
	v_mfma_f32_16x16x32_bf16 v[124:127], v[108:111], v[72:75], v[48:51]
	v_add_u32_e32 v74, s37, v78
	v_cmp_lt_i32_e32 vcc, s35, v74
	v_readlane_b32 s44, v241, 5
	v_mfma_f32_16x16x32_bf16 v[60:63], v[104:107], v[88:91], v[16:19]
	v_readlane_b32 s45, v241, 6
	v_readlane_b32 s46, v241, 7
	v_readlane_b32 s47, v241, 8
	v_add_u32_e32 v16, 0xfffff000, v74
	v_lshrrev_b32_e32 v16, 12, v16
	v_mfma_f32_16x16x32_bf16 v[152:155], v[100:103], v[88:91], v[24:27]
	v_add_u32_e32 v16, 6, v16
	v_readlane_b32 s50, v241, 11
	v_readlane_b32 s51, v241, 12
	v_or_b32_e32 v24, s38, v79
	v_mfma_f32_16x16x32_bf16 v[56:59], v[108:111], v[88:91], v[12:15]
	v_ashrrev_i32_e32 v25, 31, v24
	v_lshlrev_b64 v[72:73], 2, v[24:25]
	v_readlane_b32 s52, v241, 13
	v_cndmask_b32_e32 v12, 5, v16, vcc
	v_mad_u64_u32 v[12:13], s[18:19], v12, s30, v[70:71]
	v_mfma_f32_16x16x32_bf16 v[48:51], v[96:99], v[92:95], v[8:11]
	v_readlane_b32 s53, v241, 14
	v_readlane_b32 s54, v241, 15
	v_readlane_b32 s55, v241, 16
	v_lshl_add_u64 v[8:9], v[12:13], 0, v[72:73]
	v_lshl_add_u64 v[12:13], v[8:9], 0, v[64:65]
	v_mfma_f32_16x16x32_bf16 v[128:131], v[96:99], v[84:87], v[44:47]
	v_add_co_u32_e32 v18, vcc, s36, v12
	v_lshl_add_u64 v[16:17], v[12:13], 0, s[14:15]
	v_mfma_f32_16x16x32_bf16 v[132:135], v[100:103], v[84:87], v[40:43]
	v_addc_co_u32_e32 v19, vcc, 0, v13, vcc
	v_mfma_f32_16x16x32_bf16 v[136:139], v[104:107], v[84:87], v[36:39]
	v_mfma_f32_16x16x32_bf16 v[84:87], v[108:111], v[84:87], v[32:35]
	v_mfma_f32_16x16x32_bf16 v[140:143], v[96:99], v[88:91], v[28:31]
	ds_read_b128 v[144:147], v80 offset:49152
	ds_read_b128 v[148:151], v80 offset:50176
	ds_read_b128 v[52:55], v80 offset:51200
	ds_read_b128 v[28:31], v80 offset:52224
	ds_read_b128 v[44:47], v81 offset:49152
	ds_read_b128 v[40:43], v81 offset:50176
	ds_read_b128 v[36:39], v81 offset:51200
	ds_read_b128 v[32:35], v81 offset:52224
	s_waitcnt lgkmcnt(0)
	s_waitcnt lgkmcnt(0)
	s_barrier
	v_or_b32_e32 v96, v74, v76
	v_mfma_f32_16x16x32_bf16 v[24:27], v[100:103], v[92:95], v[4:7]
	v_or_b32_e32 v156, 16, v96
	v_or_b32_e32 v158, 32, v96
	v_or_b32_e32 v74, 48, v96
	v_mfma_f32_16x16x32_bf16 v[4:7], v[104:107], v[92:95], v[0:3]
	s_nop 2
	global_load_dwordx4 v[0:3], v[16:17], off offset:64
	global_load_dwordx4 v[12:15], v[16:17], off offset:128
	v_mfma_f32_16x16x32_bf16 v[8:11], v[108:111], v[92:95], v[20:23]
	s_nop 2
	global_load_dwordx4 v[20:23], v[18:19], off
	s_nop 0
	global_load_dwordx4 v[16:19], v[16:17], off offset:192
	s_nop 0
	v_mov_b32_e32 v228, v96
	v_ashrrev_i32_e32 v229, 31, v96
	v_lshlrev_b64 v[228:229], 12, v[228:229]
	v_lshl_add_u64 v[228:229], s[48:49], 0, v[228:229]
	v_lshl_add_u64 v[228:229], v[228:229], 0, v[72:73]
	v_lshl_add_u64 v[228:229], v[228:229], 0, v[64:65]
	v_mov_b32_e32 v230, v156
	v_ashrrev_i32_e32 v231, 31, v156
	v_lshlrev_b64 v[230:231], 12, v[230:231]
	v_lshl_add_u64 v[230:231], s[48:49], 0, v[230:231]
	v_lshl_add_u64 v[230:231], v[230:231], 0, v[72:73]
	v_lshl_add_u64 v[230:231], v[230:231], 0, v[64:65]
	v_mov_b32_e32 v232, v158
	v_ashrrev_i32_e32 v233, 31, v158
	v_lshlrev_b64 v[232:233], 12, v[232:233]
	v_lshl_add_u64 v[232:233], s[48:49], 0, v[232:233]
	v_lshl_add_u64 v[232:233], v[232:233], 0, v[72:73]
	v_lshl_add_u64 v[232:233], v[232:233], 0, v[64:65]
	v_mov_b32_e32 v234, v74
	v_ashrrev_i32_e32 v235, 31, v74
	v_lshlrev_b64 v[234:235], 12, v[234:235]
	v_lshl_add_u64 v[234:235], s[48:49], 0, v[234:235]
	v_lshl_add_u64 v[234:235], v[234:235], 0, v[72:73]
	v_lshl_add_u64 v[234:235], v[234:235], 0, v[64:65]
	global_load_dwordx4 v[162:165], v[228:229], off
	global_load_dwordx4 v[166:169], v[228:229], off offset:64
	global_load_dwordx4 v[170:173], v[228:229], off offset:128
	global_load_dwordx4 v[174:177], v[228:229], off offset:192
	global_load_dwordx4 v[178:181], v[230:231], off
	global_load_dwordx4 v[182:185], v[230:231], off offset:64
	global_load_dwordx4 v[186:189], v[230:231], off offset:128
	global_load_dwordx4 v[190:193], v[230:231], off offset:192
	global_load_dwordx4 v[194:197], v[232:233], off
	global_load_dwordx4 v[198:201], v[232:233], off offset:64
	global_load_dwordx4 v[202:205], v[232:233], off offset:128
	global_load_dwordx4 v[206:209], v[232:233], off offset:192
	global_load_dwordx4 v[210:213], v[234:235], off
	global_load_dwordx4 v[214:217], v[234:235], off offset:64
	global_load_dwordx4 v[218:221], v[234:235], off offset:128
	global_load_dwordx4 v[222:225], v[234:235], off offset:192
	v_mfma_f32_16x16x32_bf16 v[88:91], v[44:47], v[144:147], v[112:115]
	s_waitcnt vmcnt(15)
	v_pk_mul_f32 v[162:163], v[162:163], s[16:17] op_sel_hi:[1,0]
	v_mfma_f32_16x16x32_bf16 v[96:99], v[36:39], v[144:147], v[120:123]
	v_mul_f32_e64 v164, v164, s16
	v_mul_f32_e64 v165, v165, s16
	s_waitcnt vmcnt(14)
	v_pk_mul_f32 v[166:167], v[166:167], s[16:17] op_sel_hi:[1,0]
	v_pk_mul_f32 v[168:169], v[168:169], s[16:17] op_sel_hi:[1,0]
	v_mfma_f32_16x16x32_bf16 v[92:95], v[40:43], v[144:147], v[116:119]
	s_waitcnt vmcnt(13)
	v_mul_f32_e64 v170, v170, s16
	v_mul_f32_e64 v171, v171, s16
	v_pk_mul_f32 v[172:173], v[172:173], s[16:17] op_sel_hi:[1,0]
	v_pk_fma_f32 v[88:89], v[88:89], v[20:21], v[162:163]
	v_mfma_f32_16x16x32_bf16 v[104:107], v[32:35], v[144:147], v[124:127]
	v_fma_f32 v90, v90, v22, v164
	v_fma_f32 v91, v91, v23, v165
	v_pk_fma_f32 v[92:93], v[92:93], v[0:1], v[166:167]
	v_pk_fma_f32 v[94:95], v[94:95], v[2:3], v[168:169]
	v_pk_fma_f32 v[96:97], v[96:97], v[12:13], v[170:171]
	v_pk_fma_f32 v[98:99], v[98:99], v[14:15], v[172:173]
	v_mfma_f32_16x16x32_bf16 v[116:119], v[44:47], v[148:151], v[128:131]
	s_waitcnt vmcnt(12)
	v_pk_mul_f32 v[174:175], v[174:175], s[16:17] op_sel_hi:[1,0]
	v_pk_mul_f32 v[176:177], v[176:177], s[16:17] op_sel_hi:[1,0]
	v_pk_fma_f32 v[162:163], v[104:105], v[16:17], v[174:175]
	v_pk_fma_f32 v[164:165], v[106:107], v[18:19], v[176:177]
	global_store_dwordx4 v[228:229], v[88:91], off
	global_store_dwordx4 v[228:229], v[92:95], off offset:64
	global_store_dwordx4 v[228:229], v[96:99], off offset:128
	global_store_dwordx4 v[228:229], v[162:165], off offset:192
	v_mfma_f32_16x16x32_bf16 v[124:127], v[40:43], v[148:151], v[132:135]
	v_mfma_f32_16x16x32_bf16 v[92:95], v[36:39], v[148:151], v[136:139]
	s_waitcnt vmcnt(15)
	v_pk_mul_f32 v[178:179], v[178:179], s[16:17] op_sel_hi:[1,0]
	v_mfma_f32_16x16x32_bf16 v[84:87], v[32:35], v[148:151], v[84:87]
	v_mul_f32_e64 v180, v180, s16
	v_mul_f32_e64 v181, v181, s16
	s_waitcnt vmcnt(14)
	v_pk_mul_f32 v[182:183], v[182:183], s[16:17] op_sel_hi:[1,0]
	v_pk_mul_f32 v[184:185], v[184:185], s[16:17] op_sel_hi:[1,0]
	s_waitcnt vmcnt(13)
	v_pk_mul_f32 v[186:187], v[186:187], s[16:17] op_sel_hi:[1,0]
	v_pk_mul_f32 v[188:189], v[188:189], s[16:17] op_sel_hi:[1,0]
	s_waitcnt vmcnt(12)
	v_pk_mul_f32 v[190:191], v[190:191], s[16:17] op_sel_hi:[1,0]
	v_pk_mul_f32 v[192:193], v[192:193], s[16:17] op_sel_hi:[1,0]
	v_pk_fma_f32 v[178:179], v[116:117], v[20:21], v[178:179]
	v_pk_fma_f32 v[180:181], v[118:119], v[22:23], v[180:181]
	v_pk_fma_f32 v[182:183], v[124:125], v[0:1], v[182:183]
	v_pk_fma_f32 v[184:185], v[126:127], v[2:3], v[184:185]
	v_pk_fma_f32 v[92:93], v[92:93], v[12:13], v[186:187]
	v_pk_fma_f32 v[94:95], v[94:95], v[14:15], v[188:189]
	v_pk_fma_f32 v[84:85], v[84:85], v[16:17], v[190:191]
	v_pk_fma_f32 v[86:87], v[86:87], v[18:19], v[192:193]
	global_store_dwordx4 v[230:231], v[178:181], off
	global_store_dwordx4 v[230:231], v[182:185], off offset:64
	global_store_dwordx4 v[230:231], v[92:95], off offset:128
	global_store_dwordx4 v[230:231], v[84:87], off offset:192
	v_mfma_f32_16x16x32_bf16 v[166:169], v[44:47], v[52:55], v[140:143]
	v_mfma_f32_16x16x32_bf16 v[178:181], v[40:43], v[52:55], v[152:155]
	v_mfma_f32_16x16x32_bf16 v[60:63], v[36:39], v[52:55], v[60:63]
	v_mfma_f32_16x16x32_bf16 v[52:55], v[32:35], v[52:55], v[56:59]
	v_mfma_f32_16x16x32_bf16 v[44:47], v[44:47], v[28:31], v[48:51]
	s_waitcnt vmcnt(15)
	v_pk_mul_f32 v[56:57], v[194:195], s[16:17] op_sel_hi:[1,0]
	v_pk_mul_f32 v[58:59], v[196:197], s[16:17] op_sel_hi:[1,0]
	s_waitcnt vmcnt(14)
	v_pk_mul_f32 v[194:195], v[198:199], s[16:17] op_sel_hi:[1,0]
	v_pk_mul_f32 v[196:197], v[200:201], s[16:17] op_sel_hi:[1,0]
	s_waitcnt vmcnt(13)
	v_pk_mul_f32 v[198:199], v[202:203], s[16:17] op_sel_hi:[1,0]
	v_pk_mul_f32 v[200:201], v[204:205], s[16:17] op_sel_hi:[1,0]
	s_waitcnt vmcnt(12)
	v_pk_mul_f32 v[202:203], v[206:207], s[16:17] op_sel_hi:[1,0]
	v_pk_mul_f32 v[204:205], v[208:209], s[16:17] op_sel_hi:[1,0]
	v_pk_fma_f32 v[56:57], v[166:167], v[20:21], v[56:57]
	v_pk_fma_f32 v[58:59], v[168:169], v[22:23], v[58:59]
	v_pk_fma_f32 v[194:195], v[178:179], v[0:1], v[194:195]
	v_pk_fma_f32 v[196:197], v[180:181], v[2:3], v[196:197]
	v_pk_fma_f32 v[60:61], v[60:61], v[12:13], v[198:199]
	v_pk_fma_f32 v[62:63], v[62:63], v[14:15], v[200:201]
	v_pk_fma_f32 v[52:53], v[52:53], v[16:17], v[202:203]
	v_pk_fma_f32 v[54:55], v[54:55], v[18:19], v[204:205]
	global_store_dwordx4 v[232:233], v[56:59], off
	global_store_dwordx4 v[232:233], v[194:197], off offset:64
	global_store_dwordx4 v[232:233], v[60:63], off offset:128
	global_store_dwordx4 v[232:233], v[52:55], off offset:192
	v_mfma_f32_16x16x32_bf16 v[24:27], v[40:43], v[28:31], v[24:27]
	v_mfma_f32_16x16x32_bf16 v[4:7], v[36:39], v[28:31], v[4:7]
	s_add_i32 s17, s17, s34
	s_cmpk_gt_i32 s2, 0x9f
	s_waitcnt vmcnt(13)
	v_pk_mul_f32 v[36:37], v[218:219], s[16:17] op_sel_hi:[1,0]
	v_mfma_f32_16x16x32_bf16 v[8:11], v[32:35], v[28:31], v[8:11]
	v_mul_f32_e64 v28, v210, s16
	v_mul_f32_e64 v29, v211, s16
	v_pk_mul_f32 v[30:31], v[212:213], s[16:17] op_sel_hi:[1,0]
	v_pk_mul_f32 v[32:33], v[214:215], s[16:17] op_sel_hi:[1,0]
	v_pk_mul_f32 v[34:35], v[216:217], s[16:17] op_sel_hi:[1,0]
	v_pk_mul_f32 v[38:39], v[220:221], s[16:17] op_sel_hi:[1,0]
	s_waitcnt vmcnt(12)
	v_pk_mul_f32 v[222:223], v[222:223], s[16:17] op_sel_hi:[1,0]
	v_pk_mul_f32 v[224:225], v[224:225], s[16:17] op_sel_hi:[1,0]
	v_pk_fma_f32 v[20:21], v[44:45], v[20:21], v[28:29]
	v_pk_fma_f32 v[22:23], v[46:47], v[22:23], v[30:31]
	v_pk_fma_f32 v[0:1], v[24:25], v[0:1], v[32:33]
	v_pk_fma_f32 v[2:3], v[26:27], v[2:3], v[34:35]
	v_pk_fma_f32 v[4:5], v[4:5], v[12:13], v[36:37]
	v_pk_fma_f32 v[6:7], v[6:7], v[14:15], v[38:39]
	v_pk_fma_f32 v[8:9], v[8:9], v[16:17], v[222:223]
	v_pk_fma_f32 v[10:11], v[10:11], v[18:19], v[224:225]
	global_store_dwordx4 v[234:235], v[20:23], off
	global_store_dwordx4 v[234:235], v[0:3], off offset:64
	global_store_dwordx4 v[234:235], v[4:7], off offset:128
	global_store_dwordx4 v[234:235], v[8:11], off offset:192
	s_cbranch_scc0 .LBB0_3062
